# GEMM DMA via SGPR base + 32-bit lane offset (all address stepping on SALU), DMA issue moved to MFMA gaps without LDS reads
# speedup vs baseline: 1.0962x; 1.0101x over previous
.LBB0_91:
	s_lshr_b32 s8, s10, 3
	s_and_b32 s8, s8, 0xffffff8
	s_and_b32 s9, s10, 7
	s_or_b32 s8, s8, s9
	s_and_b32 s9, s10, 56
	v_readlane_b32 s0, v252, 42
	s_or_b32 s11, s9, s0
	v_mov_b32_e32 v6, v171
	s_lshl_b32 s9, s11, 19
	v_lshlrev_b32_e32 v2, 3, v6
	s_add_u32 s12, s98, s9
	v_ashrrev_i32_e32 v3, 31, v2
	s_addc_u32 s13, s99, 0
	v_lshlrev_b64 v[4:5], 1, v[2:3]
	s_mov_b32 s9, s15
	v_lshl_add_u64 v[154:155], s[12:13], 0, v[4:5]
	s_mov_b64 s[74:75], s[12:13]
	s_lshl_b64 s[12:13], s[8:9], 18
	v_readlane_b32 s0, v252, 36
	v_readlane_b32 s1, v252, 37
	s_add_u32 s12, s0, s12
	s_addc_u32 s13, s1, s13
	v_lshrrev_b32_e32 v3, 2, v6
	v_and_b32_e32 v0, 24, v2
	v_lshl_add_u64 v[156:157], s[12:13], 0, v[4:5]
	s_mov_b64 s[76:77], s[12:13]
	v_mad_u64_u32 v[158:159], s[12:13], v3, 40, v[0:1]
	s_movk_i32 s0, 0x50
	v_and_b32_e32 v2, 0x30, v6
	v_xor_b32_e32 v140, v4, v2
	v_xor_b32_e32 v154, v154, v2
	v_xor_b32_e32 v156, v156, v2
	v_and_b32_e32 v130, 31, v6
	v_lshlrev_b32_e32 v130, 6, v130
	v_lshrrev_b32_e32 v131, 2, v6
	v_and_b32_e32 v131, 3, v131
	v_bfe_u32 v133, v6, 5, 1
	v_xor_b32_e32 v131, v131, v133
	v_lshl_or_b32 v130, v131, 4, v130
	v_lshrrev_b32_e32 v131, 7, v6
	v_lshl_or_b32 v132, v131, 13, v130
	v_bfe_u32 v131, v6, 6, 1
	v_lshl_or_b32 v133, v131, 12, v130
	v_or_b32_e32 v133, 0x4000, v133
	v_xor_b32_e32 v134, 32, v132
	v_xor_b32_e32 v135, 32, v133
	v_lshrrev_b32_e32 v131, 6, v6
	s_nop 1
	v_readfirstlane_b32 s72, v131
	s_nop 3
	s_lshl_b32 s72, s72, 10
	s_waitcnt lgkmcnt(0)
	s_barrier
	s_mov_b32 s14, 0
	s_lshl_b64 s[12:13], s[14:15], 14
	s_add_u32 s12, s12, s74
	s_addc_u32 s13, s13, s75
	s_add_u32 m0, s72, 0x0
	s_nop 0
	global_load_lds_dwordx4 v140, s[12:13]
	s_add_u32 m0, m0, 0x1000
	s_add_u32 s12, s12, 0x1000
	s_addc_u32 s13, s13, 0
	global_load_lds_dwordx4 v140, s[12:13]
	s_add_u32 m0, m0, 0x1000
	s_add_u32 s12, s12, 0x1000
	s_addc_u32 s13, s13, 0
	global_load_lds_dwordx4 v140, s[12:13]
	s_add_u32 m0, m0, 0x1000
	s_add_u32 s12, s12, 0x1000
	s_addc_u32 s13, s13, 0
	global_load_lds_dwordx4 v140, s[12:13]
	s_add_u32 m0, m0, 0x1000
	s_lshl_b64 s[12:13], s[14:15], 13
	s_add_u32 s12, s12, s76
	s_addc_u32 s13, s13, s77
	global_load_lds_dwordx4 v140, s[12:13]
	s_add_u32 m0, m0, 0x1000
	s_add_u32 s12, s12, 0x1000
	s_addc_u32 s13, s13, 0
	global_load_lds_dwordx4 v140, s[12:13]
	s_mov_b32 s14, 1
	s_lshl_b64 s[12:13], s[14:15], 14
	s_add_u32 s12, s12, s74
	s_addc_u32 s13, s13, s75
	s_add_u32 m0, s72, 0x6000
	s_nop 0
	global_load_lds_dwordx4 v140, s[12:13]
	s_add_u32 m0, m0, 0x1000
	s_add_u32 s12, s12, 0x1000
	s_addc_u32 s13, s13, 0
	global_load_lds_dwordx4 v140, s[12:13]
	s_add_u32 m0, m0, 0x1000
	s_add_u32 s12, s12, 0x1000
	s_addc_u32 s13, s13, 0
	global_load_lds_dwordx4 v140, s[12:13]
	s_add_u32 m0, m0, 0x1000
	s_add_u32 s12, s12, 0x1000
	s_addc_u32 s13, s13, 0
	global_load_lds_dwordx4 v140, s[12:13]
	s_add_u32 m0, m0, 0x1000
	s_lshl_b64 s[12:13], s[14:15], 13
	s_add_u32 s12, s12, s76
	s_addc_u32 s13, s13, s77
	global_load_lds_dwordx4 v140, s[12:13]
	s_add_u32 m0, m0, 0x1000
	s_add_u32 s12, s12, 0x1000
	s_addc_u32 s13, s13, 0
	global_load_lds_dwordx4 v140, s[12:13]
	s_mov_b32 s14, 2
	s_lshl_b64 s[12:13], s[14:15], 14
	s_add_u32 s12, s12, s74
	s_addc_u32 s13, s13, s75
	s_add_u32 m0, s72, 0xc000
	s_nop 0
	global_load_lds_dwordx4 v140, s[12:13]
	s_add_u32 m0, m0, 0x1000
	s_add_u32 s12, s12, 0x1000
	s_addc_u32 s13, s13, 0
	global_load_lds_dwordx4 v140, s[12:13]
	s_add_u32 m0, m0, 0x1000
	s_add_u32 s12, s12, 0x1000
	s_addc_u32 s13, s13, 0
	global_load_lds_dwordx4 v140, s[12:13]
	s_add_u32 m0, m0, 0x1000
	s_add_u32 s12, s12, 0x1000
	s_addc_u32 s13, s13, 0
	global_load_lds_dwordx4 v140, s[12:13]
	s_add_u32 m0, m0, 0x1000
	s_lshl_b64 s[12:13], s[14:15], 13
	s_add_u32 s12, s12, s76
	s_addc_u32 s13, s13, s77
	global_load_lds_dwordx4 v140, s[12:13]
	s_add_u32 m0, m0, 0x1000
	s_add_u32 s12, s12, 0x1000
	s_addc_u32 s13, s13, 0
	global_load_lds_dwordx4 v140, s[12:13]
	v_and_b32_e32 v2, 0xfffff9f, v6
	v_mul_lo_u32 v160, v2, s0
	v_or_b32_e32 v2, 0x60, v6
	v_lshrrev_b32_e32 v0, 1, v6
	v_and_b32_e32 v3, 0x5f, v6
	v_mul_lo_u32 v161, v2, s0
	v_mov_b32_e32 v2, 0
	s_mov_b32 s9, 0
	v_and_b32_e32 v0, 16, v0
	v_mul_u32_u24_e32 v159, 0x50, v3
	v_mov_b32_e32 v3, v2
	v_mov_b32_e32 v4, v2
	v_mov_b32_e32 v5, v2
	v_mov_b32_e32 v6, v2
	v_mov_b32_e32 v7, v2
	v_mov_b32_e32 v8, v2
	v_mov_b32_e32 v9, v2
	v_mov_b32_e32 v10, v2
	v_mov_b32_e32 v11, v2
	v_mov_b32_e32 v12, v2
	v_mov_b32_e32 v13, v2
	v_mov_b32_e32 v14, v2
	v_mov_b32_e32 v15, v2
	v_mov_b32_e32 v16, v2
	v_mov_b32_e32 v17, v2
	v_mov_b32_e32 v18, v2
	v_mov_b32_e32 v19, v2
	v_mov_b32_e32 v20, v2
	v_mov_b32_e32 v21, v2
	v_mov_b32_e32 v22, v2
	v_mov_b32_e32 v23, v2
	v_mov_b32_e32 v24, v2
	v_mov_b32_e32 v25, v2
	v_mov_b32_e32 v26, v2
	v_mov_b32_e32 v27, v2
	v_mov_b32_e32 v28, v2
	v_mov_b32_e32 v29, v2
	v_mov_b32_e32 v30, v2
	v_mov_b32_e32 v31, v2
	v_mov_b32_e32 v32, v2
	v_mov_b32_e32 v33, v2
	v_mov_b32_e32 v34, v2
	v_mov_b32_e32 v35, v2
	v_mov_b32_e32 v36, v2
	v_mov_b32_e32 v37, v2
	v_mov_b32_e32 v38, v2
	v_mov_b32_e32 v39, v2
	v_mov_b32_e32 v40, v2
	v_mov_b32_e32 v41, v2
	v_mov_b32_e32 v42, v2
	v_mov_b32_e32 v43, v2
	v_mov_b32_e32 v44, v2
	v_mov_b32_e32 v45, v2
	v_mov_b32_e32 v46, v2
	v_mov_b32_e32 v47, v2
	v_mov_b32_e32 v48, v2
	v_mov_b32_e32 v49, v2
	v_mov_b32_e32 v50, v2
	v_mov_b32_e32 v51, v2
	v_mov_b32_e32 v52, v2
	v_mov_b32_e32 v53, v2
	v_mov_b32_e32 v54, v2
	v_mov_b32_e32 v55, v2
	v_mov_b32_e32 v56, v2
	v_mov_b32_e32 v57, v2
	v_mov_b32_e32 v58, v2
	v_mov_b32_e32 v59, v2
	v_mov_b32_e32 v60, v2
	v_mov_b32_e32 v61, v2
	v_mov_b32_e32 v62, v2
	v_mov_b32_e32 v63, v2
	v_mov_b32_e32 v64, v2
	v_mov_b32_e32 v65, v2
	v_mov_b32_e32 v66, v2
	v_mov_b32_e32 v67, v2
	v_mov_b32_e32 v68, v2
	v_mov_b32_e32 v69, v2
	v_mov_b32_e32 v70, v2
	v_mov_b32_e32 v71, v2
	v_mov_b32_e32 v72, v2
	v_mov_b32_e32 v73, v2
	v_mov_b32_e32 v74, v2
	v_mov_b32_e32 v75, v2
	v_mov_b32_e32 v76, v2
	v_mov_b32_e32 v77, v2
	v_mov_b32_e32 v78, v2
	v_mov_b32_e32 v79, v2
	v_mov_b32_e32 v80, v2
	v_mov_b32_e32 v81, v2
	s_waitcnt vmcnt(17)
	v_mov_b32_e32 v82, v2
	v_mov_b32_e32 v83, v2
	v_mov_b32_e32 v84, v2
	v_mov_b32_e32 v85, v2
	s_waitcnt vmcnt(16)
	v_mov_b32_e32 v86, v2
	v_mov_b32_e32 v87, v2
	v_mov_b32_e32 v88, v2
	v_mov_b32_e32 v89, v2
	s_waitcnt vmcnt(15)
	v_mov_b32_e32 v90, v2
	v_mov_b32_e32 v91, v2
	v_mov_b32_e32 v92, v2
	v_mov_b32_e32 v93, v2
	s_waitcnt vmcnt(14)
	v_mov_b32_e32 v94, v2
	v_mov_b32_e32 v95, v2
	v_mov_b32_e32 v96, v2
	v_mov_b32_e32 v97, v2
	v_mov_b32_e32 v98, v2
	v_mov_b32_e32 v99, v2
	v_mov_b32_e32 v100, v2
	v_mov_b32_e32 v101, v2
	v_mov_b32_e32 v102, v2
	v_mov_b32_e32 v103, v2
	v_mov_b32_e32 v104, v2
	v_mov_b32_e32 v105, v2
	v_mov_b32_e32 v106, v2
	v_mov_b32_e32 v107, v2
	v_mov_b32_e32 v108, v2
	v_mov_b32_e32 v109, v2
	v_mov_b32_e32 v110, v2
	v_mov_b32_e32 v111, v2
	v_mov_b32_e32 v112, v2
	v_mov_b32_e32 v113, v2
	v_mov_b32_e32 v114, v2
	v_mov_b32_e32 v115, v2
	v_mov_b32_e32 v116, v2
	v_mov_b32_e32 v117, v2
	v_mov_b32_e32 v118, v2
	v_mov_b32_e32 v119, v2
	v_mov_b32_e32 v120, v2
	v_mov_b32_e32 v121, v2
	v_mov_b32_e32 v122, v2
	v_mov_b32_e32 v123, v2
	v_mov_b32_e32 v124, v2
	v_mov_b32_e32 v125, v2
	v_mov_b32_e32 v126, v2
	v_mov_b32_e32 v127, v2
	v_mov_b32_e32 v128, v2
	v_mov_b32_e32 v129, v2
	s_mov_b32 s9, 0
	s_mov_b32 s34, 0
	v_mov_b32_e32 v138, v132
	v_mov_b32_e32 v139, v133
	s_waitcnt vmcnt(12)
	s_barrier
	ds_read_b128 v[162:165], v138 offset:0
	ds_read_b128 v[228:231], v139 offset:0
	ds_read_b128 v[236:239], v139 offset:2048
	ds_read_b128 v[204:207], v138 offset:2048
	ds_read_b128 v[212:215], v138 offset:4096
	ds_read_b128 v[220:223], v138 offset:6144
.Lg92_loop:
	v_add_u32_e32 v136, s34, v134
	v_add_u32_e32 v137, s34, v135
	s_add_i32 s9, s9, 1
	s_add_u32 s73, s34, 0x6000
	s_cmp_lt_u32 s73, 0x12000
	s_cselect_b32 s73, s73, 0
	v_add_u32_e32 v138, s73, v132
	v_add_u32_e32 v139, s73, v133
	s_waitcnt lgkmcnt(0)
	v_mfma_f32_32x32x16_bf16 v[114:129], v[162:165], v[228:231], v[114:129]
	ds_read_b128 v[166:169], v136 offset:0
	ds_read_b128 v[232:235], v137 offset:0
	s_add_i32 s14, s9, 2
	s_lshl_b64 s[12:13], s[14:15], 14
	s_add_u32 s12, s12, s74
	v_mfma_f32_32x32x16_bf16 v[98:113], v[162:165], v[236:239], v[98:113]
	ds_read_b128 v[240:243], v137 offset:2048
	ds_read_b128 v[208:211], v136 offset:2048
	s_addc_u32 s13, s13, s75
	v_mfma_f32_32x32x16_bf16 v[82:97], v[204:207], v[228:231], v[82:97]
	ds_read_b128 v[216:219], v136 offset:4096
	ds_read_b128 v[224:227], v136 offset:6144
	v_mfma_f32_32x32x16_bf16 v[66:81], v[204:207], v[236:239], v[66:81]
	v_mfma_f32_32x32x16_bf16 v[50:65], v[212:215], v[228:231], v[50:65]
	v_mfma_f32_32x32x16_bf16 v[34:49], v[212:215], v[236:239], v[34:49]
	v_mfma_f32_32x32x16_bf16 v[18:33], v[220:223], v[228:231], v[18:33]
	v_mfma_f32_32x32x16_bf16 v[2:17], v[220:223], v[236:239], v[2:17]
	s_waitcnt vmcnt(6) lgkmcnt(0)
	s_barrier
	s_add_u32 m0, s34, s72
	v_mfma_f32_32x32x16_bf16 v[114:129], v[166:169], v[232:235], v[114:129]
	ds_read_b128 v[162:165], v138 offset:0
	ds_read_b128 v[228:231], v139 offset:0
	v_mfma_f32_32x32x16_bf16 v[98:113], v[166:169], v[240:243], v[98:113]
	ds_read_b128 v[236:239], v139 offset:2048
	ds_read_b128 v[204:207], v138 offset:2048
	v_mfma_f32_32x32x16_bf16 v[82:97], v[208:211], v[232:235], v[82:97]
	ds_read_b128 v[212:215], v138 offset:4096
	ds_read_b128 v[220:223], v138 offset:6144
	v_mfma_f32_32x32x16_bf16 v[66:81], v[208:211], v[240:243], v[66:81]
	global_load_lds_dwordx4 v140, s[12:13]
	s_add_u32 m0, m0, 0x1000
	s_add_u32 s12, s12, 0x1000
	s_addc_u32 s13, s13, 0
	v_mfma_f32_32x32x16_bf16 v[50:65], v[216:219], v[232:235], v[50:65]
	global_load_lds_dwordx4 v140, s[12:13]
	s_add_u32 m0, m0, 0x1000
	s_add_u32 s12, s12, 0x1000
	s_addc_u32 s13, s13, 0
	v_mfma_f32_32x32x16_bf16 v[34:49], v[216:219], v[240:243], v[34:49]
	global_load_lds_dwordx4 v140, s[12:13]
	s_add_u32 m0, m0, 0x1000
	s_add_u32 s12, s12, 0x1000
	s_addc_u32 s13, s13, 0
	v_mfma_f32_32x32x16_bf16 v[18:33], v[224:227], v[232:235], v[18:33]
	global_load_lds_dwordx4 v140, s[12:13]
	s_add_u32 m0, m0, 0x1000
	s_lshl_b64 s[12:13], s[14:15], 13
	s_add_u32 s12, s12, s76
	s_addc_u32 s13, s13, s77
	v_mfma_f32_32x32x16_bf16 v[2:17], v[224:227], v[240:243], v[2:17]
	global_load_lds_dwordx4 v140, s[12:13]
	s_add_u32 m0, m0, 0x1000
	s_add_u32 s12, s12, 0x1000
	s_addc_u32 s13, s13, 0
	s_nop 0
	global_load_lds_dwordx4 v140, s[12:13]
	s_mov_b32 s34, s73
	s_cmp_lg_u32 s9, 29
	s_cbranch_scc1 .Lg92_loop
	v_add_u32_e32 v136, s34, v134
	v_add_u32_e32 v137, s34, v135
	s_add_i32 s9, s9, 1
	s_add_u32 s73, s34, 0x6000
	s_cmp_lt_u32 s73, 0x12000
	s_cselect_b32 s73, s73, 0
	v_add_u32_e32 v138, s73, v132
	v_add_u32_e32 v139, s73, v133
	s_waitcnt lgkmcnt(0)
	v_mfma_f32_32x32x16_bf16 v[114:129], v[162:165], v[228:231], v[114:129]
	ds_read_b128 v[166:169], v136 offset:0
	ds_read_b128 v[232:235], v137 offset:0
	v_mfma_f32_32x32x16_bf16 v[98:113], v[162:165], v[236:239], v[98:113]
	ds_read_b128 v[240:243], v137 offset:2048
	ds_read_b128 v[208:211], v136 offset:2048
	v_mfma_f32_32x32x16_bf16 v[82:97], v[204:207], v[228:231], v[82:97]
	ds_read_b128 v[216:219], v136 offset:4096
	ds_read_b128 v[224:227], v136 offset:6144
	v_mfma_f32_32x32x16_bf16 v[66:81], v[204:207], v[236:239], v[66:81]
	v_mfma_f32_32x32x16_bf16 v[50:65], v[212:215], v[228:231], v[50:65]
	v_mfma_f32_32x32x16_bf16 v[34:49], v[212:215], v[236:239], v[34:49]
	v_mfma_f32_32x32x16_bf16 v[18:33], v[220:223], v[228:231], v[18:33]
	v_mfma_f32_32x32x16_bf16 v[2:17], v[220:223], v[236:239], v[2:17]
	s_waitcnt vmcnt(6) lgkmcnt(0)
	s_barrier
	v_mfma_f32_32x32x16_bf16 v[114:129], v[166:169], v[232:235], v[114:129]
	ds_read_b128 v[162:165], v138 offset:0
	ds_read_b128 v[228:231], v139 offset:0
	v_mfma_f32_32x32x16_bf16 v[98:113], v[166:169], v[240:243], v[98:113]
	ds_read_b128 v[236:239], v139 offset:2048
	ds_read_b128 v[204:207], v138 offset:2048
	v_mfma_f32_32x32x16_bf16 v[82:97], v[208:211], v[232:235], v[82:97]
	ds_read_b128 v[212:215], v138 offset:4096
	ds_read_b128 v[220:223], v138 offset:6144
	v_mfma_f32_32x32x16_bf16 v[66:81], v[208:211], v[240:243], v[66:81]
	v_mfma_f32_32x32x16_bf16 v[50:65], v[216:219], v[232:235], v[50:65]
	v_mfma_f32_32x32x16_bf16 v[34:49], v[216:219], v[240:243], v[34:49]
	v_mfma_f32_32x32x16_bf16 v[18:33], v[224:227], v[232:235], v[18:33]
	v_mfma_f32_32x32x16_bf16 v[2:17], v[224:227], v[240:243], v[2:17]
	s_mov_b32 s34, s73
	v_add_u32_e32 v136, s34, v134
	v_add_u32_e32 v137, s34, v135
	s_add_i32 s9, s9, 1
	s_add_u32 s73, s34, 0x6000
	s_cmp_lt_u32 s73, 0x12000
	s_cselect_b32 s73, s73, 0
	v_add_u32_e32 v138, s73, v132
	v_add_u32_e32 v139, s73, v133
	s_waitcnt lgkmcnt(0)
	v_mfma_f32_32x32x16_bf16 v[114:129], v[162:165], v[228:231], v[114:129]
	ds_read_b128 v[166:169], v136 offset:0
	ds_read_b128 v[232:235], v137 offset:0
	v_mfma_f32_32x32x16_bf16 v[98:113], v[162:165], v[236:239], v[98:113]
	ds_read_b128 v[240:243], v137 offset:2048
	ds_read_b128 v[208:211], v136 offset:2048
	v_mfma_f32_32x32x16_bf16 v[82:97], v[204:207], v[228:231], v[82:97]
	ds_read_b128 v[216:219], v136 offset:4096
	ds_read_b128 v[224:227], v136 offset:6144
	v_mfma_f32_32x32x16_bf16 v[66:81], v[204:207], v[236:239], v[66:81]
	v_mfma_f32_32x32x16_bf16 v[50:65], v[212:215], v[228:231], v[50:65]
	v_mfma_f32_32x32x16_bf16 v[34:49], v[212:215], v[236:239], v[34:49]
	v_mfma_f32_32x32x16_bf16 v[18:33], v[220:223], v[228:231], v[18:33]
	v_mfma_f32_32x32x16_bf16 v[2:17], v[220:223], v[236:239], v[2:17]
	s_waitcnt vmcnt(0) lgkmcnt(0)
	s_barrier
	v_mfma_f32_32x32x16_bf16 v[114:129], v[166:169], v[232:235], v[114:129]
	ds_read_b128 v[162:165], v138 offset:0
	ds_read_b128 v[228:231], v139 offset:0
	v_mfma_f32_32x32x16_bf16 v[98:113], v[166:169], v[240:243], v[98:113]
	ds_read_b128 v[236:239], v139 offset:2048
	ds_read_b128 v[204:207], v138 offset:2048
	v_mfma_f32_32x32x16_bf16 v[82:97], v[208:211], v[232:235], v[82:97]
	ds_read_b128 v[212:215], v138 offset:4096
	ds_read_b128 v[220:223], v138 offset:6144
	v_mfma_f32_32x32x16_bf16 v[66:81], v[208:211], v[240:243], v[66:81]
	v_mfma_f32_32x32x16_bf16 v[50:65], v[216:219], v[232:235], v[50:65]
	v_mfma_f32_32x32x16_bf16 v[34:49], v[216:219], v[240:243], v[34:49]
	v_mfma_f32_32x32x16_bf16 v[18:33], v[224:227], v[232:235], v[18:33]
	v_mfma_f32_32x32x16_bf16 v[2:17], v[224:227], v[240:243], v[2:17]
	s_mov_b32 s34, s73
	v_add_u32_e32 v136, s34, v134
	v_add_u32_e32 v137, s34, v135
	s_add_i32 s9, s9, 1
	s_waitcnt lgkmcnt(0)
	v_mfma_f32_32x32x16_bf16 v[114:129], v[162:165], v[228:231], v[114:129]
	ds_read_b128 v[166:169], v136 offset:0
	ds_read_b128 v[232:235], v137 offset:0
	v_mfma_f32_32x32x16_bf16 v[98:113], v[162:165], v[236:239], v[98:113]
	ds_read_b128 v[240:243], v137 offset:2048
	ds_read_b128 v[208:211], v136 offset:2048
	v_mfma_f32_32x32x16_bf16 v[82:97], v[204:207], v[228:231], v[82:97]
	ds_read_b128 v[216:219], v136 offset:4096
	ds_read_b128 v[224:227], v136 offset:6144
	v_mfma_f32_32x32x16_bf16 v[66:81], v[204:207], v[236:239], v[66:81]
	v_mfma_f32_32x32x16_bf16 v[50:65], v[212:215], v[228:231], v[50:65]
	v_mfma_f32_32x32x16_bf16 v[34:49], v[212:215], v[236:239], v[34:49]
	v_mfma_f32_32x32x16_bf16 v[18:33], v[220:223], v[228:231], v[18:33]
	v_mfma_f32_32x32x16_bf16 v[2:17], v[220:223], v[236:239], v[2:17]
	s_waitcnt lgkmcnt(0)
	v_mfma_f32_32x32x16_bf16 v[114:129], v[166:169], v[232:235], v[114:129]
	v_mfma_f32_32x32x16_bf16 v[98:113], v[166:169], v[240:243], v[98:113]
	v_mfma_f32_32x32x16_bf16 v[82:97], v[208:211], v[232:235], v[82:97]
	v_mfma_f32_32x32x16_bf16 v[66:81], v[208:211], v[240:243], v[66:81]
	v_mfma_f32_32x32x16_bf16 v[50:65], v[216:219], v[232:235], v[50:65]
	v_mfma_f32_32x32x16_bf16 v[34:49], v[216:219], v[240:243], v[34:49]
	v_mfma_f32_32x32x16_bf16 v[18:33], v[224:227], v[232:235], v[18:33]
	v_mfma_f32_32x32x16_bf16 v[2:17], v[224:227], v[240:243], v[2:17]
	s_mov_b32 s14, 31
	s_lshl_b64 s[12:13], s[14:15], 13
	s_movk_i32 s34, 0x7800
	s_movk_i32 s72, 0x6000
	s_mov_b32 s73, 0xc000
	s_movk_i32 s74, 0x104
	s_mov_b32 s75, 0x42ce8ed0
	s_mov_b32 s76, 0xbfb8aa3b
	s_mov_b32 s77, 0x1d730000
	v_mov_b32_e32 v0, v171
	s_barrier
	s_waitcnt vmcnt(4)
	v_lshrrev_b32_e32 v130, 1, v0
	v_and_b32_e32 v130, 0xfffffc0, v130
	v_lshrrev_b32_e32 v131, 3, v0
	v_and_or_b32 v130, v131, 4, v130
	v_and_b32_e32 v0, 0x5f, v0
	v_mul_lo_u32 v130, v130, s53
	v_lshl_add_u32 v0, v0, 2, v130
	s_barrier
	ds_write2_b32 v0, v114, v98 offset1:32
	ds_write2_b32 v0, v115, v99 offset0:132 offset1:164
	v_add_u32_e32 v98, 0x400, v0
	ds_write2_b32 v98, v116, v100 offset0:8 offset1:40
	ds_write2_b32 v98, v117, v101 offset0:140 offset1:172
	v_add_u32_e32 v98, 0x1000, v0
	ds_write2_b32 v98, v118, v102 offset0:32 offset1:64
	ds_write2_b32 v98, v119, v103 offset0:164 offset1:196
	v_add_u32_e32 v98, 0x1400, v0
	ds_write2_b32 v98, v120, v104 offset0:40 offset1:72
	ds_write2_b32 v98, v121, v105 offset0:172 offset1:204
	v_add_u32_e32 v98, 0x2000, v0
	ds_write2_b32 v98, v122, v106 offset0:64 offset1:96
	ds_write2_b32 v98, v123, v107 offset0:196 offset1:228
	v_add_u32_e32 v98, 0x2400, v0
	ds_write2_b32 v98, v124, v108 offset0:72 offset1:104
	ds_write2_b32 v98, v125, v109 offset0:204 offset1:236
	v_add_u32_e32 v98, 0x3000, v0
	ds_write2_b32 v98, v126, v110 offset0:96 offset1:128
	v_add_u32_e32 v98, 0x3200, v0
	ds_write2_b32 v98, v127, v111 offset0:100 offset1:132
	v_add_u32_e32 v98, 0x3400, v0
	ds_write2_b32 v98, v128, v112 offset0:104 offset1:136
	v_add_u32_e32 v98, 0x3600, v0
	ds_write2_b32 v98, v129, v113 offset0:108 offset1:140
	v_add_u32_e32 v98, 0x4000, v0
	ds_write2_b32 v98, v82, v66 offset0:128 offset1:160
	v_add_u32_e32 v66, 0x4400, v0
	ds_write2_b32 v66, v83, v67 offset0:4 offset1:36
	ds_write2_b32 v66, v84, v68 offset0:136 offset1:168
	v_add_u32_e32 v66, 0x4800, v0
	ds_write2_b32 v66, v85, v69 offset0:12 offset1:44
	v_add_u32_e32 v66, 0x5000, v0
	ds_write2_b32 v66, v86, v70 offset0:160 offset1:192
	v_add_u32_e32 v66, 0x5400, v0
	ds_write2_b32 v66, v87, v71 offset0:36 offset1:68
	ds_write2_b32 v66, v88, v72 offset0:168 offset1:200
	v_add_u32_e32 v66, 0x5800, v0
	ds_write2_b32 v66, v89, v73 offset0:44 offset1:76
	v_add_u32_e32 v66, 0x6000, v0
	ds_write2_b32 v66, v90, v74 offset0:192 offset1:224
	v_add_u32_e32 v66, 0x6400, v0
	ds_write2_b32 v66, v91, v75 offset0:68 offset1:100
	ds_write2_b32 v66, v92, v76 offset0:200 offset1:232
	v_add_u32_e32 v66, 0x6800, v0
	ds_write2_b32 v66, v93, v77 offset0:76 offset1:108
	v_add_u32_e32 v66, 0x7200, v0
	ds_write2_b32 v66, v94, v78 offset0:96 offset1:128
	v_add_u32_e32 v66, 0x7400, v0
	ds_write2_b32 v66, v95, v79 offset0:100 offset1:132
	v_add_u32_e32 v66, 0x7600, v0
	v_add_u32_e32 v0, 0x7800, v0
	v_mov_b32_e32 v74, v171
	ds_write2_b32 v66, v96, v80 offset0:104 offset1:136
	ds_write2_b32 v0, v97, v81 offset0:108 offset1:140
	s_waitcnt lgkmcnt(0)
	s_barrier
	s_lshl_b32 s8, s8, 7
	v_lshlrev_b32_e32 v75, 3, v74
	v_and_b32_e32 v0, 0x78, v75
	v_or_b32_e32 v0, s8, v0
	v_lshl_add_u64 v[70:71], v[0:1], 2, s[6:7]
	global_load_dwordx4 v[66:69], v[70:71], off
	s_nop 0
	global_load_dwordx4 v[70:73], v[70:71], off offset:16
	v_ashrrev_i32_e32 v76, 4, v74
	v_lshrrev_b32_e32 v77, 5, v0
	v_and_b32_e32 v0, 24, v75
	v_mul_lo_u32 v75, v76, s53
	v_and_b32_e32 v74, 15, v74
	v_readlane_b32 s0, v252, 46
	s_lshl_b32 s9, s11, 8
	v_lshl_add_u32 v78, v74, 5, v75
	v_lshlrev_b32_e32 v79, 1, v76
	s_mov_b32 s11, 0
	v_lshlrev_b32_e32 v74, 1, v0
	v_readlane_b32 s1, v252, 47
	s_waitcnt vmcnt(0)

.LBB0_356:
	s_lshr_b32 s6, s12, 3
	s_and_b32 s8, s12, 56
	v_readlane_b32 s0, v252, 42
	s_and_b32 s6, s6, 0xffffff8
	s_and_b32 s7, s12, 7
	s_or_b32 s9, s8, s0
	v_mov_b32_e32 v6, v171
	s_or_b32 s6, s6, s7
	s_lshl_b32 s7, s9, 19
	v_lshlrev_b32_e32 v2, 3, v6
	s_add_u32 s10, s98, s7
	v_ashrrev_i32_e32 v3, 31, v2
	s_addc_u32 s11, s99, 0
	v_lshlrev_b64 v[4:5], 1, v[2:3]
	s_mov_b32 s7, s15
	v_lshl_add_u64 v[154:155], s[10:11], 0, v[4:5]
	s_mov_b64 s[74:75], s[10:11]
	s_lshl_b64 s[10:11], s[6:7], 18
	v_readlane_b32 s0, v252, 38
	v_readlane_b32 s1, v252, 39
	s_add_u32 s10, s0, s10
	s_addc_u32 s11, s1, s11
	v_lshrrev_b32_e32 v3, 2, v6
	v_and_b32_e32 v0, 24, v2
	v_lshl_add_u64 v[156:157], s[10:11], 0, v[4:5]
	s_mov_b64 s[76:77], s[10:11]
	v_mad_u64_u32 v[158:159], s[10:11], v3, 40, v[0:1]
	s_movk_i32 s0, 0x50
	v_and_b32_e32 v2, 0x30, v6
	v_xor_b32_e32 v140, v4, v2
	v_xor_b32_e32 v154, v154, v2
	v_xor_b32_e32 v156, v156, v2
	v_and_b32_e32 v130, 31, v6
	v_lshlrev_b32_e32 v130, 6, v130
	v_lshrrev_b32_e32 v131, 2, v6
	v_and_b32_e32 v131, 3, v131
	v_bfe_u32 v133, v6, 5, 1
	v_xor_b32_e32 v131, v131, v133
	v_lshl_or_b32 v130, v131, 4, v130
	v_lshrrev_b32_e32 v131, 7, v6
	v_lshl_or_b32 v132, v131, 13, v130
	v_bfe_u32 v131, v6, 6, 1
	v_lshl_or_b32 v133, v131, 12, v130
	v_or_b32_e32 v133, 0x4000, v133
	v_xor_b32_e32 v134, 32, v132
	v_xor_b32_e32 v135, 32, v133
	v_lshrrev_b32_e32 v131, 6, v6
	s_nop 1
	v_readfirstlane_b32 s72, v131
	s_nop 3
	s_lshl_b32 s72, s72, 10
	s_waitcnt lgkmcnt(0)
	s_barrier
	s_mov_b32 s14, 0
	s_lshl_b64 s[10:11], s[14:15], 14
	s_add_u32 s10, s10, s74
	s_addc_u32 s11, s11, s75
	s_add_u32 m0, s72, 0x0
	s_nop 0
	global_load_lds_dwordx4 v140, s[10:11]
	s_add_u32 m0, m0, 0x1000
	s_add_u32 s10, s10, 0x1000
	s_addc_u32 s11, s11, 0
	global_load_lds_dwordx4 v140, s[10:11]
	s_add_u32 m0, m0, 0x1000
	s_add_u32 s10, s10, 0x1000
	s_addc_u32 s11, s11, 0
	global_load_lds_dwordx4 v140, s[10:11]
	s_add_u32 m0, m0, 0x1000
	s_add_u32 s10, s10, 0x1000
	s_addc_u32 s11, s11, 0
	global_load_lds_dwordx4 v140, s[10:11]
	s_add_u32 m0, m0, 0x1000
	s_lshl_b64 s[10:11], s[14:15], 13
	s_add_u32 s10, s10, s76
	s_addc_u32 s11, s11, s77
	global_load_lds_dwordx4 v140, s[10:11]
	s_add_u32 m0, m0, 0x1000
	s_add_u32 s10, s10, 0x1000
	s_addc_u32 s11, s11, 0
	global_load_lds_dwordx4 v140, s[10:11]
	s_mov_b32 s14, 1
	s_lshl_b64 s[10:11], s[14:15], 14
	s_add_u32 s10, s10, s74
	s_addc_u32 s11, s11, s75
	s_add_u32 m0, s72, 0x6000
	s_nop 0
	global_load_lds_dwordx4 v140, s[10:11]
	s_add_u32 m0, m0, 0x1000
	s_add_u32 s10, s10, 0x1000
	s_addc_u32 s11, s11, 0
	global_load_lds_dwordx4 v140, s[10:11]
	s_add_u32 m0, m0, 0x1000
	s_add_u32 s10, s10, 0x1000
	s_addc_u32 s11, s11, 0
	global_load_lds_dwordx4 v140, s[10:11]
	s_add_u32 m0, m0, 0x1000
	s_add_u32 s10, s10, 0x1000
	s_addc_u32 s11, s11, 0
	global_load_lds_dwordx4 v140, s[10:11]
	s_add_u32 m0, m0, 0x1000
	s_lshl_b64 s[10:11], s[14:15], 13
	s_add_u32 s10, s10, s76
	s_addc_u32 s11, s11, s77
	global_load_lds_dwordx4 v140, s[10:11]
	s_add_u32 m0, m0, 0x1000
	s_add_u32 s10, s10, 0x1000
	s_addc_u32 s11, s11, 0
	global_load_lds_dwordx4 v140, s[10:11]
	s_mov_b32 s14, 2
	s_lshl_b64 s[10:11], s[14:15], 14
	s_add_u32 s10, s10, s74
	s_addc_u32 s11, s11, s75
	s_add_u32 m0, s72, 0xc000
	s_nop 0
	global_load_lds_dwordx4 v140, s[10:11]
	s_add_u32 m0, m0, 0x1000
	s_add_u32 s10, s10, 0x1000
	s_addc_u32 s11, s11, 0
	global_load_lds_dwordx4 v140, s[10:11]
	s_add_u32 m0, m0, 0x1000
	s_add_u32 s10, s10, 0x1000
	s_addc_u32 s11, s11, 0
	global_load_lds_dwordx4 v140, s[10:11]
	s_add_u32 m0, m0, 0x1000
	s_add_u32 s10, s10, 0x1000
	s_addc_u32 s11, s11, 0
	global_load_lds_dwordx4 v140, s[10:11]
	s_add_u32 m0, m0, 0x1000
	s_lshl_b64 s[10:11], s[14:15], 13
	s_add_u32 s10, s10, s76
	s_addc_u32 s11, s11, s77
	global_load_lds_dwordx4 v140, s[10:11]
	s_add_u32 m0, m0, 0x1000
	s_add_u32 s10, s10, 0x1000
	s_addc_u32 s11, s11, 0
	global_load_lds_dwordx4 v140, s[10:11]
	v_and_b32_e32 v2, 0xfffff9f, v6
	v_mul_lo_u32 v160, v2, s0
	v_or_b32_e32 v2, 0x60, v6
	v_lshrrev_b32_e32 v0, 1, v6
	v_and_b32_e32 v3, 0x5f, v6
	v_mul_lo_u32 v161, v2, s0
	v_mov_b32_e32 v2, 0
	s_mov_b32 s7, 0
	v_and_b32_e32 v0, 16, v0
	v_mul_u32_u24_e32 v159, 0x50, v3
	v_mov_b32_e32 v3, v2
	v_mov_b32_e32 v4, v2
	v_mov_b32_e32 v5, v2
	v_mov_b32_e32 v6, v2
	v_mov_b32_e32 v7, v2
	v_mov_b32_e32 v8, v2
	v_mov_b32_e32 v9, v2
	v_mov_b32_e32 v10, v2
	v_mov_b32_e32 v11, v2
	v_mov_b32_e32 v12, v2
	v_mov_b32_e32 v13, v2
	v_mov_b32_e32 v14, v2
	v_mov_b32_e32 v15, v2
	v_mov_b32_e32 v16, v2
	v_mov_b32_e32 v17, v2
	v_mov_b32_e32 v18, v2
	v_mov_b32_e32 v19, v2
	v_mov_b32_e32 v20, v2
	v_mov_b32_e32 v21, v2
	v_mov_b32_e32 v22, v2
	v_mov_b32_e32 v23, v2
	v_mov_b32_e32 v24, v2
	v_mov_b32_e32 v25, v2
	v_mov_b32_e32 v26, v2
	v_mov_b32_e32 v27, v2
	v_mov_b32_e32 v28, v2
	v_mov_b32_e32 v29, v2
	v_mov_b32_e32 v30, v2
	v_mov_b32_e32 v31, v2
	v_mov_b32_e32 v32, v2
	v_mov_b32_e32 v33, v2
	v_mov_b32_e32 v34, v2
	v_mov_b32_e32 v35, v2
	v_mov_b32_e32 v36, v2
	v_mov_b32_e32 v37, v2
	v_mov_b32_e32 v38, v2
	v_mov_b32_e32 v39, v2
	v_mov_b32_e32 v40, v2
	v_mov_b32_e32 v41, v2
	v_mov_b32_e32 v42, v2
	v_mov_b32_e32 v43, v2
	v_mov_b32_e32 v44, v2
	v_mov_b32_e32 v45, v2
	v_mov_b32_e32 v46, v2
	v_mov_b32_e32 v47, v2
	v_mov_b32_e32 v48, v2
	v_mov_b32_e32 v49, v2
	v_mov_b32_e32 v50, v2
	v_mov_b32_e32 v51, v2
	v_mov_b32_e32 v52, v2
	v_mov_b32_e32 v53, v2
	v_mov_b32_e32 v54, v2
	v_mov_b32_e32 v55, v2
	v_mov_b32_e32 v56, v2
	v_mov_b32_e32 v57, v2
	v_mov_b32_e32 v58, v2
	v_mov_b32_e32 v59, v2
	v_mov_b32_e32 v60, v2
	v_mov_b32_e32 v61, v2
	v_mov_b32_e32 v62, v2
	v_mov_b32_e32 v63, v2
	v_mov_b32_e32 v64, v2
	v_mov_b32_e32 v65, v2
	v_mov_b32_e32 v66, v2
	v_mov_b32_e32 v67, v2
	v_mov_b32_e32 v68, v2
	v_mov_b32_e32 v69, v2
	v_mov_b32_e32 v70, v2
	v_mov_b32_e32 v71, v2
	v_mov_b32_e32 v72, v2
	v_mov_b32_e32 v73, v2
	v_mov_b32_e32 v74, v2
	v_mov_b32_e32 v75, v2
	v_mov_b32_e32 v76, v2
	v_mov_b32_e32 v77, v2
	v_mov_b32_e32 v78, v2
	v_mov_b32_e32 v79, v2
	v_mov_b32_e32 v80, v2
	v_mov_b32_e32 v81, v2
	s_waitcnt vmcnt(17)
	v_mov_b32_e32 v82, v2
	v_mov_b32_e32 v83, v2
	v_mov_b32_e32 v84, v2
	v_mov_b32_e32 v85, v2
	s_waitcnt vmcnt(16)
	v_mov_b32_e32 v86, v2
	v_mov_b32_e32 v87, v2
	v_mov_b32_e32 v88, v2
	v_mov_b32_e32 v89, v2
	s_waitcnt vmcnt(15)
	v_mov_b32_e32 v90, v2
	v_mov_b32_e32 v91, v2
	v_mov_b32_e32 v92, v2
	v_mov_b32_e32 v93, v2
	s_waitcnt vmcnt(14)
	v_mov_b32_e32 v94, v2
	v_mov_b32_e32 v95, v2
	v_mov_b32_e32 v96, v2
	v_mov_b32_e32 v97, v2
	v_mov_b32_e32 v98, v2
	v_mov_b32_e32 v99, v2
	v_mov_b32_e32 v100, v2
	v_mov_b32_e32 v101, v2
	v_mov_b32_e32 v102, v2
	v_mov_b32_e32 v103, v2
	v_mov_b32_e32 v104, v2
	v_mov_b32_e32 v105, v2
	v_mov_b32_e32 v106, v2
	v_mov_b32_e32 v107, v2
	v_mov_b32_e32 v108, v2
	v_mov_b32_e32 v109, v2
	v_mov_b32_e32 v110, v2
	v_mov_b32_e32 v111, v2
	v_mov_b32_e32 v112, v2
	v_mov_b32_e32 v113, v2
	v_mov_b32_e32 v114, v2
	v_mov_b32_e32 v115, v2
	v_mov_b32_e32 v116, v2
	v_mov_b32_e32 v117, v2
	v_mov_b32_e32 v118, v2
	v_mov_b32_e32 v119, v2
	v_mov_b32_e32 v120, v2
	v_mov_b32_e32 v121, v2
	v_mov_b32_e32 v122, v2
	v_mov_b32_e32 v123, v2
	v_mov_b32_e32 v124, v2
	v_mov_b32_e32 v125, v2
	v_mov_b32_e32 v126, v2
	v_mov_b32_e32 v127, v2
	v_mov_b32_e32 v128, v2
	v_mov_b32_e32 v129, v2
	s_mov_b32 s7, 0
	s_mov_b32 s13, 0
	v_mov_b32_e32 v138, v132
	v_mov_b32_e32 v139, v133
	s_waitcnt vmcnt(12)
	s_barrier
	ds_read_b128 v[162:165], v138 offset:0
	ds_read_b128 v[228:231], v139 offset:0
	ds_read_b128 v[236:239], v139 offset:2048
	ds_read_b128 v[204:207], v138 offset:2048
	ds_read_b128 v[212:215], v138 offset:4096
	ds_read_b128 v[220:223], v138 offset:6144
.Lg357_loop:
	v_add_u32_e32 v136, s13, v134
	v_add_u32_e32 v137, s13, v135
	s_add_i32 s7, s7, 1
	s_add_u32 s73, s13, 0x6000
	s_cmp_lt_u32 s73, 0x12000
	s_cselect_b32 s73, s73, 0
	v_add_u32_e32 v138, s73, v132
	v_add_u32_e32 v139, s73, v133
	s_waitcnt lgkmcnt(0)
	v_mfma_f32_32x32x16_bf16 v[114:129], v[162:165], v[228:231], v[114:129]
	ds_read_b128 v[166:169], v136 offset:0
	ds_read_b128 v[232:235], v137 offset:0
	s_add_i32 s14, s7, 2
	s_lshl_b64 s[10:11], s[14:15], 14
	s_add_u32 s10, s10, s74
	v_mfma_f32_32x32x16_bf16 v[98:113], v[162:165], v[236:239], v[98:113]
	ds_read_b128 v[240:243], v137 offset:2048
	ds_read_b128 v[208:211], v136 offset:2048
	s_addc_u32 s11, s11, s75
	v_mfma_f32_32x32x16_bf16 v[82:97], v[204:207], v[228:231], v[82:97]
	ds_read_b128 v[216:219], v136 offset:4096
	ds_read_b128 v[224:227], v136 offset:6144
	v_mfma_f32_32x32x16_bf16 v[66:81], v[204:207], v[236:239], v[66:81]
	v_mfma_f32_32x32x16_bf16 v[50:65], v[212:215], v[228:231], v[50:65]
	v_mfma_f32_32x32x16_bf16 v[34:49], v[212:215], v[236:239], v[34:49]
	v_mfma_f32_32x32x16_bf16 v[18:33], v[220:223], v[228:231], v[18:33]
	v_mfma_f32_32x32x16_bf16 v[2:17], v[220:223], v[236:239], v[2:17]
	s_waitcnt vmcnt(6) lgkmcnt(0)
	s_barrier
	s_add_u32 m0, s13, s72
	v_mfma_f32_32x32x16_bf16 v[114:129], v[166:169], v[232:235], v[114:129]
	ds_read_b128 v[162:165], v138 offset:0
	ds_read_b128 v[228:231], v139 offset:0
	v_mfma_f32_32x32x16_bf16 v[98:113], v[166:169], v[240:243], v[98:113]
	ds_read_b128 v[236:239], v139 offset:2048
	ds_read_b128 v[204:207], v138 offset:2048
	v_mfma_f32_32x32x16_bf16 v[82:97], v[208:211], v[232:235], v[82:97]
	ds_read_b128 v[212:215], v138 offset:4096
	ds_read_b128 v[220:223], v138 offset:6144
	v_mfma_f32_32x32x16_bf16 v[66:81], v[208:211], v[240:243], v[66:81]
	global_load_lds_dwordx4 v140, s[10:11]
	s_add_u32 m0, m0, 0x1000
	s_add_u32 s10, s10, 0x1000
	s_addc_u32 s11, s11, 0
	v_mfma_f32_32x32x16_bf16 v[50:65], v[216:219], v[232:235], v[50:65]
	global_load_lds_dwordx4 v140, s[10:11]
	s_add_u32 m0, m0, 0x1000
	s_add_u32 s10, s10, 0x1000
	s_addc_u32 s11, s11, 0
	v_mfma_f32_32x32x16_bf16 v[34:49], v[216:219], v[240:243], v[34:49]
	global_load_lds_dwordx4 v140, s[10:11]
	s_add_u32 m0, m0, 0x1000
	s_add_u32 s10, s10, 0x1000
	s_addc_u32 s11, s11, 0
	v_mfma_f32_32x32x16_bf16 v[18:33], v[224:227], v[232:235], v[18:33]
	global_load_lds_dwordx4 v140, s[10:11]
	s_add_u32 m0, m0, 0x1000
	s_lshl_b64 s[10:11], s[14:15], 13
	s_add_u32 s10, s10, s76
	s_addc_u32 s11, s11, s77
	v_mfma_f32_32x32x16_bf16 v[2:17], v[224:227], v[240:243], v[2:17]
	global_load_lds_dwordx4 v140, s[10:11]
	s_add_u32 m0, m0, 0x1000
	s_add_u32 s10, s10, 0x1000
	s_addc_u32 s11, s11, 0
	s_nop 0
	global_load_lds_dwordx4 v140, s[10:11]
	s_mov_b32 s13, s73
	s_cmp_lg_u32 s7, 29
	s_cbranch_scc1 .Lg357_loop
	v_add_u32_e32 v136, s13, v134
	v_add_u32_e32 v137, s13, v135
	s_add_i32 s7, s7, 1
	s_add_u32 s73, s13, 0x6000
	s_cmp_lt_u32 s73, 0x12000
	s_cselect_b32 s73, s73, 0
	v_add_u32_e32 v138, s73, v132
	v_add_u32_e32 v139, s73, v133
	s_waitcnt lgkmcnt(0)
	v_mfma_f32_32x32x16_bf16 v[114:129], v[162:165], v[228:231], v[114:129]
	ds_read_b128 v[166:169], v136 offset:0
	ds_read_b128 v[232:235], v137 offset:0
	v_mfma_f32_32x32x16_bf16 v[98:113], v[162:165], v[236:239], v[98:113]
	ds_read_b128 v[240:243], v137 offset:2048
	ds_read_b128 v[208:211], v136 offset:2048
	v_mfma_f32_32x32x16_bf16 v[82:97], v[204:207], v[228:231], v[82:97]
	ds_read_b128 v[216:219], v136 offset:4096
	ds_read_b128 v[224:227], v136 offset:6144
	v_mfma_f32_32x32x16_bf16 v[66:81], v[204:207], v[236:239], v[66:81]
	v_mfma_f32_32x32x16_bf16 v[50:65], v[212:215], v[228:231], v[50:65]
	v_mfma_f32_32x32x16_bf16 v[34:49], v[212:215], v[236:239], v[34:49]
	v_mfma_f32_32x32x16_bf16 v[18:33], v[220:223], v[228:231], v[18:33]
	v_mfma_f32_32x32x16_bf16 v[2:17], v[220:223], v[236:239], v[2:17]
	s_waitcnt vmcnt(6) lgkmcnt(0)
	s_barrier
	v_mfma_f32_32x32x16_bf16 v[114:129], v[166:169], v[232:235], v[114:129]
	ds_read_b128 v[162:165], v138 offset:0
	ds_read_b128 v[228:231], v139 offset:0
	v_mfma_f32_32x32x16_bf16 v[98:113], v[166:169], v[240:243], v[98:113]
	ds_read_b128 v[236:239], v139 offset:2048
	ds_read_b128 v[204:207], v138 offset:2048
	v_mfma_f32_32x32x16_bf16 v[82:97], v[208:211], v[232:235], v[82:97]
	ds_read_b128 v[212:215], v138 offset:4096
	ds_read_b128 v[220:223], v138 offset:6144
	v_mfma_f32_32x32x16_bf16 v[66:81], v[208:211], v[240:243], v[66:81]
	v_mfma_f32_32x32x16_bf16 v[50:65], v[216:219], v[232:235], v[50:65]
	v_mfma_f32_32x32x16_bf16 v[34:49], v[216:219], v[240:243], v[34:49]
	v_mfma_f32_32x32x16_bf16 v[18:33], v[224:227], v[232:235], v[18:33]
	v_mfma_f32_32x32x16_bf16 v[2:17], v[224:227], v[240:243], v[2:17]
	s_mov_b32 s13, s73
	v_add_u32_e32 v136, s13, v134
	v_add_u32_e32 v137, s13, v135
	s_add_i32 s7, s7, 1
	s_add_u32 s73, s13, 0x6000
	s_cmp_lt_u32 s73, 0x12000
	s_cselect_b32 s73, s73, 0
	v_add_u32_e32 v138, s73, v132
	v_add_u32_e32 v139, s73, v133
	s_waitcnt lgkmcnt(0)
	v_mfma_f32_32x32x16_bf16 v[114:129], v[162:165], v[228:231], v[114:129]
	ds_read_b128 v[166:169], v136 offset:0
	ds_read_b128 v[232:235], v137 offset:0
	v_mfma_f32_32x32x16_bf16 v[98:113], v[162:165], v[236:239], v[98:113]
	ds_read_b128 v[240:243], v137 offset:2048
	ds_read_b128 v[208:211], v136 offset:2048
	v_mfma_f32_32x32x16_bf16 v[82:97], v[204:207], v[228:231], v[82:97]
	ds_read_b128 v[216:219], v136 offset:4096
	ds_read_b128 v[224:227], v136 offset:6144
	v_mfma_f32_32x32x16_bf16 v[66:81], v[204:207], v[236:239], v[66:81]
	v_mfma_f32_32x32x16_bf16 v[50:65], v[212:215], v[228:231], v[50:65]
	v_mfma_f32_32x32x16_bf16 v[34:49], v[212:215], v[236:239], v[34:49]
	v_mfma_f32_32x32x16_bf16 v[18:33], v[220:223], v[228:231], v[18:33]
	v_mfma_f32_32x32x16_bf16 v[2:17], v[220:223], v[236:239], v[2:17]
	s_waitcnt vmcnt(0) lgkmcnt(0)
	s_barrier
	v_mfma_f32_32x32x16_bf16 v[114:129], v[166:169], v[232:235], v[114:129]
	ds_read_b128 v[162:165], v138 offset:0
	ds_read_b128 v[228:231], v139 offset:0
	v_mfma_f32_32x32x16_bf16 v[98:113], v[166:169], v[240:243], v[98:113]
	ds_read_b128 v[236:239], v139 offset:2048
	ds_read_b128 v[204:207], v138 offset:2048
	v_mfma_f32_32x32x16_bf16 v[82:97], v[208:211], v[232:235], v[82:97]
	ds_read_b128 v[212:215], v138 offset:4096
	ds_read_b128 v[220:223], v138 offset:6144
	v_mfma_f32_32x32x16_bf16 v[66:81], v[208:211], v[240:243], v[66:81]
	v_mfma_f32_32x32x16_bf16 v[50:65], v[216:219], v[232:235], v[50:65]
	v_mfma_f32_32x32x16_bf16 v[34:49], v[216:219], v[240:243], v[34:49]
	v_mfma_f32_32x32x16_bf16 v[18:33], v[224:227], v[232:235], v[18:33]
	v_mfma_f32_32x32x16_bf16 v[2:17], v[224:227], v[240:243], v[2:17]
	s_mov_b32 s13, s73
	v_add_u32_e32 v136, s13, v134
	v_add_u32_e32 v137, s13, v135
	s_add_i32 s7, s7, 1
	s_waitcnt lgkmcnt(0)
	v_mfma_f32_32x32x16_bf16 v[114:129], v[162:165], v[228:231], v[114:129]
	ds_read_b128 v[166:169], v136 offset:0
	ds_read_b128 v[232:235], v137 offset:0
	v_mfma_f32_32x32x16_bf16 v[98:113], v[162:165], v[236:239], v[98:113]
	ds_read_b128 v[240:243], v137 offset:2048
	ds_read_b128 v[208:211], v136 offset:2048
	v_mfma_f32_32x32x16_bf16 v[82:97], v[204:207], v[228:231], v[82:97]
	ds_read_b128 v[216:219], v136 offset:4096
	ds_read_b128 v[224:227], v136 offset:6144
	v_mfma_f32_32x32x16_bf16 v[66:81], v[204:207], v[236:239], v[66:81]
	v_mfma_f32_32x32x16_bf16 v[50:65], v[212:215], v[228:231], v[50:65]
	v_mfma_f32_32x32x16_bf16 v[34:49], v[212:215], v[236:239], v[34:49]
	v_mfma_f32_32x32x16_bf16 v[18:33], v[220:223], v[228:231], v[18:33]
	v_mfma_f32_32x32x16_bf16 v[2:17], v[220:223], v[236:239], v[2:17]
	s_waitcnt lgkmcnt(0)
	v_mfma_f32_32x32x16_bf16 v[114:129], v[166:169], v[232:235], v[114:129]
	v_mfma_f32_32x32x16_bf16 v[98:113], v[166:169], v[240:243], v[98:113]
	v_mfma_f32_32x32x16_bf16 v[82:97], v[208:211], v[232:235], v[82:97]
	v_mfma_f32_32x32x16_bf16 v[66:81], v[208:211], v[240:243], v[66:81]
	v_mfma_f32_32x32x16_bf16 v[50:65], v[216:219], v[232:235], v[50:65]
	v_mfma_f32_32x32x16_bf16 v[34:49], v[216:219], v[240:243], v[34:49]
	v_mfma_f32_32x32x16_bf16 v[18:33], v[224:227], v[232:235], v[18:33]
	v_mfma_f32_32x32x16_bf16 v[2:17], v[224:227], v[240:243], v[2:17]
	s_mov_b32 s14, 31
	s_lshl_b64 s[10:11], s[14:15], 13
	s_movk_i32 s13, 0x7800
	s_movk_i32 s72, 0x6000
	s_mov_b32 s73, 0xc000
	s_movk_i32 s74, 0x104
	s_mov_b32 s75, 0x42ce8ed0
	s_mov_b32 s76, 0xbfb8aa3b
	s_mov_b32 s77, 0x1d730000
	v_mov_b32_e32 v0, v171
	s_barrier
	s_waitcnt vmcnt(4)
	v_lshrrev_b32_e32 v130, 1, v0
	v_and_b32_e32 v130, 0xfffffc0, v130
	v_lshrrev_b32_e32 v131, 3, v0
	v_and_or_b32 v130, v131, 4, v130
	v_and_b32_e32 v0, 0x5f, v0
	v_mul_lo_u32 v130, v130, s53
	v_lshl_add_u32 v0, v0, 2, v130
	s_barrier
	ds_write2_b32 v0, v114, v98 offset1:32
	ds_write2_b32 v0, v115, v99 offset0:132 offset1:164
	v_add_u32_e32 v98, 0x400, v0
	ds_write2_b32 v98, v116, v100 offset0:8 offset1:40
	ds_write2_b32 v98, v117, v101 offset0:140 offset1:172
	v_add_u32_e32 v98, 0x1000, v0
	ds_write2_b32 v98, v118, v102 offset0:32 offset1:64
	ds_write2_b32 v98, v119, v103 offset0:164 offset1:196
	v_add_u32_e32 v98, 0x1400, v0
	ds_write2_b32 v98, v120, v104 offset0:40 offset1:72
	ds_write2_b32 v98, v121, v105 offset0:172 offset1:204
	v_add_u32_e32 v98, 0x2000, v0
	ds_write2_b32 v98, v122, v106 offset0:64 offset1:96
	ds_write2_b32 v98, v123, v107 offset0:196 offset1:228
	v_add_u32_e32 v98, 0x2400, v0
	ds_write2_b32 v98, v124, v108 offset0:72 offset1:104
	ds_write2_b32 v98, v125, v109 offset0:204 offset1:236
	v_add_u32_e32 v98, 0x3000, v0
	ds_write2_b32 v98, v126, v110 offset0:96 offset1:128
	v_add_u32_e32 v98, 0x3200, v0
	ds_write2_b32 v98, v127, v111 offset0:100 offset1:132
	v_add_u32_e32 v98, 0x3400, v0
	ds_write2_b32 v98, v128, v112 offset0:104 offset1:136
	v_add_u32_e32 v98, 0x3600, v0
	ds_write2_b32 v98, v129, v113 offset0:108 offset1:140
	v_add_u32_e32 v98, 0x4000, v0
	ds_write2_b32 v98, v82, v66 offset0:128 offset1:160
	v_add_u32_e32 v66, 0x4400, v0
	ds_write2_b32 v66, v83, v67 offset0:4 offset1:36
	ds_write2_b32 v66, v84, v68 offset0:136 offset1:168
	v_add_u32_e32 v66, 0x4800, v0
	ds_write2_b32 v66, v85, v69 offset0:12 offset1:44
	v_add_u32_e32 v66, 0x5000, v0
	s_lshl_b32 s13, s9, 8
	ds_write2_b32 v66, v86, v70 offset0:160 offset1:192
	v_add_u32_e32 v66, 0x5400, v0
	s_lshl_b32 s34, s6, 7
	ds_write2_b32 v66, v87, v71 offset0:36 offset1:68
	ds_write2_b32 v66, v88, v72 offset0:168 offset1:200
	v_add_u32_e32 v66, 0x5800, v0
	s_add_i32 s6, s13, 0xffffe000
	ds_write2_b32 v66, v89, v73 offset0:44 offset1:76
	v_add_u32_e32 v66, 0x6000, v0
	s_lshr_b32 s6, s6, 12
	ds_write2_b32 v66, v90, v74 offset0:192 offset1:224
	v_add_u32_e32 v66, 0x6400, v0
	s_mulk_i32 s6, 0x1800
	ds_write2_b32 v66, v91, v75 offset0:68 offset1:100
	ds_write2_b32 v66, v92, v76 offset0:200 offset1:232
	v_add_u32_e32 v66, 0x6800, v0
	s_addk_i32 s6, 0x1800
	ds_write2_b32 v66, v93, v77 offset0:76 offset1:108
	v_add_u32_e32 v66, 0x7200, v0
	s_cmp_gt_u32 s8, 31
	ds_write2_b32 v66, v94, v78 offset0:96 offset1:128
	v_add_u32_e32 v66, 0x7400, v0
	s_cselect_b32 s14, s6, 0
	ds_write2_b32 v66, v95, v79 offset0:100 offset1:132
	v_add_u32_e32 v66, 0x7600, v0
	v_add_u32_e32 v0, 0x7800, v0
	v_mov_b32_e32 v76, v171
	s_lshl_b64 s[6:7], s[14:15], 2
	ds_write2_b32 v66, v96, v80 offset0:104 offset1:136
	ds_write2_b32 v0, v97, v81 offset0:108 offset1:140
	s_waitcnt lgkmcnt(0)
	s_barrier
	s_add_u32 s6, s61, s6
	v_lshlrev_b32_e32 v0, 3, v76
	v_and_b32_e32 v0, 0x78, v0
	s_addc_u32 s7, s79, s7
	v_or_b32_e32 v0, s34, v0
	s_add_u32 s8, s6, 0x1d642000
	s_addc_u32 s9, s7, 0
	v_lshlrev_b64 v[74:75], 2, v[0:1]
	v_lshl_add_u64 v[70:71], s[8:9], 0, v[74:75]
	global_load_dwordx4 v[66:69], v[70:71], off offset:16
	s_nop 0
	global_load_dwordx4 v[70:73], v[70:71], off
	v_ashrrev_i32_e32 v90, 4, v76
	v_lshl_add_u64 v[82:83], s[56:57], 0, v[74:75]
	v_mul_lo_u32 v74, v90, s53
	v_and_b32_e32 v75, 15, v76
	s_mov_b32 s14, 0
	v_lshl_add_u32 v91, v75, 5, v74
	v_lshlrev_b32_e32 v92, 1, v90
	s_branch .LBB0_360

.LBB0_431:
	s_lshr_b32 s6, s79, 3
	s_and_b32 s8, s79, 56
	v_readlane_b32 s0, v252, 42
	s_and_b32 s7, s79, 7
	s_or_b32 s43, s8, s0
	s_and_b32 s40, s6, 56
	v_mov_b32_e32 v6, v171
	s_or_b32 s42, s40, s7
	s_lshl_b32 s6, s43, 19
	v_lshlrev_b32_e32 v2, 3, v6
	s_add_u32 s6, s98, s6
	v_ashrrev_i32_e32 v3, 31, v2
	s_addc_u32 s7, s99, 0
	v_lshlrev_b64 v[4:5], 1, v[2:3]
	v_lshl_add_u64 v[154:155], s[6:7], 0, v[4:5]
	s_mov_b64 s[74:75], s[6:7]
	s_lshl_b32 s6, s42, 18
	s_add_u32 s6, s92, s6
	s_addc_u32 s7, s93, 0
	v_lshrrev_b32_e32 v3, 2, v6
	v_and_b32_e32 v0, 24, v2
	v_lshl_add_u64 v[156:157], s[6:7], 0, v[4:5]
	s_mov_b64 s[76:77], s[6:7]
	v_mad_u64_u32 v[158:159], s[6:7], v3, 40, v[0:1]
	s_movk_i32 s0, 0x50
	v_and_b32_e32 v2, 0x30, v6
	v_xor_b32_e32 v140, v4, v2
	v_xor_b32_e32 v154, v154, v2
	v_xor_b32_e32 v156, v156, v2
	v_and_b32_e32 v130, 31, v6
	v_lshlrev_b32_e32 v130, 6, v130
	v_lshrrev_b32_e32 v131, 2, v6
	v_and_b32_e32 v131, 3, v131
	v_bfe_u32 v133, v6, 5, 1
	v_xor_b32_e32 v131, v131, v133
	v_lshl_or_b32 v130, v131, 4, v130
	v_lshrrev_b32_e32 v131, 7, v6
	v_lshl_or_b32 v132, v131, 13, v130
	v_bfe_u32 v131, v6, 6, 1
	v_lshl_or_b32 v133, v131, 12, v130
	v_or_b32_e32 v133, 0x4000, v133
	v_xor_b32_e32 v134, 32, v132
	v_xor_b32_e32 v135, 32, v133
	v_lshrrev_b32_e32 v131, 6, v6
	s_nop 1
	v_readfirstlane_b32 s72, v131
	s_nop 3
	s_lshl_b32 s72, s72, 10
	s_waitcnt lgkmcnt(0)
	s_barrier
	s_mov_b32 s14, 0
	s_lshl_b64 s[12:13], s[14:15], 14
	s_add_u32 s12, s12, s74
	s_addc_u32 s13, s13, s75
	s_add_u32 m0, s72, 0x0
	s_nop 0
	global_load_lds_dwordx4 v140, s[12:13]
	s_add_u32 m0, m0, 0x1000
	s_add_u32 s12, s12, 0x1000
	s_addc_u32 s13, s13, 0
	global_load_lds_dwordx4 v140, s[12:13]
	s_add_u32 m0, m0, 0x1000
	s_add_u32 s12, s12, 0x1000
	s_addc_u32 s13, s13, 0
	global_load_lds_dwordx4 v140, s[12:13]
	s_add_u32 m0, m0, 0x1000
	s_add_u32 s12, s12, 0x1000
	s_addc_u32 s13, s13, 0
	global_load_lds_dwordx4 v140, s[12:13]
	s_add_u32 m0, m0, 0x1000
	s_lshl_b64 s[12:13], s[14:15], 13
	s_add_u32 s12, s12, s76
	s_addc_u32 s13, s13, s77
	global_load_lds_dwordx4 v140, s[12:13]
	s_add_u32 m0, m0, 0x1000
	s_add_u32 s12, s12, 0x1000
	s_addc_u32 s13, s13, 0
	global_load_lds_dwordx4 v140, s[12:13]
	s_mov_b32 s14, 1
	s_lshl_b64 s[12:13], s[14:15], 14
	s_add_u32 s12, s12, s74
	s_addc_u32 s13, s13, s75
	s_add_u32 m0, s72, 0x6000
	s_nop 0
	global_load_lds_dwordx4 v140, s[12:13]
	s_add_u32 m0, m0, 0x1000
	s_add_u32 s12, s12, 0x1000
	s_addc_u32 s13, s13, 0
	global_load_lds_dwordx4 v140, s[12:13]
	s_add_u32 m0, m0, 0x1000
	s_add_u32 s12, s12, 0x1000
	s_addc_u32 s13, s13, 0
	global_load_lds_dwordx4 v140, s[12:13]
	s_add_u32 m0, m0, 0x1000
	s_add_u32 s12, s12, 0x1000
	s_addc_u32 s13, s13, 0
	global_load_lds_dwordx4 v140, s[12:13]
	s_add_u32 m0, m0, 0x1000
	s_lshl_b64 s[12:13], s[14:15], 13
	s_add_u32 s12, s12, s76
	s_addc_u32 s13, s13, s77
	global_load_lds_dwordx4 v140, s[12:13]
	s_add_u32 m0, m0, 0x1000
	s_add_u32 s12, s12, 0x1000
	s_addc_u32 s13, s13, 0
	global_load_lds_dwordx4 v140, s[12:13]
	s_mov_b32 s14, 2
	s_lshl_b64 s[12:13], s[14:15], 14
	s_add_u32 s12, s12, s74
	s_addc_u32 s13, s13, s75
	s_add_u32 m0, s72, 0xc000
	s_nop 0
	global_load_lds_dwordx4 v140, s[12:13]
	s_add_u32 m0, m0, 0x1000
	s_add_u32 s12, s12, 0x1000
	s_addc_u32 s13, s13, 0
	global_load_lds_dwordx4 v140, s[12:13]
	s_add_u32 m0, m0, 0x1000
	s_add_u32 s12, s12, 0x1000
	s_addc_u32 s13, s13, 0
	global_load_lds_dwordx4 v140, s[12:13]
	s_add_u32 m0, m0, 0x1000
	s_add_u32 s12, s12, 0x1000
	s_addc_u32 s13, s13, 0
	global_load_lds_dwordx4 v140, s[12:13]
	s_add_u32 m0, m0, 0x1000
	s_lshl_b64 s[12:13], s[14:15], 13
	s_add_u32 s12, s12, s76
	s_addc_u32 s13, s13, s77
	global_load_lds_dwordx4 v140, s[12:13]
	s_add_u32 m0, m0, 0x1000
	s_add_u32 s12, s12, 0x1000
	s_addc_u32 s13, s13, 0
	global_load_lds_dwordx4 v140, s[12:13]
	v_and_b32_e32 v2, 0xfffff9f, v6
	v_mul_lo_u32 v160, v2, s0
	v_or_b32_e32 v2, 0x60, v6
	v_lshrrev_b32_e32 v0, 1, v6
	v_and_b32_e32 v3, 0x5f, v6
	v_mul_lo_u32 v161, v2, s0
	v_mov_b32_e32 v2, 0
	s_mov_b32 s6, 0
	v_and_b32_e32 v0, 16, v0
	v_mul_u32_u24_e32 v159, 0x50, v3
	v_mov_b32_e32 v3, v2
	v_mov_b32_e32 v4, v2
	v_mov_b32_e32 v5, v2
	v_mov_b32_e32 v6, v2
	v_mov_b32_e32 v7, v2
	v_mov_b32_e32 v8, v2
	v_mov_b32_e32 v9, v2
	v_mov_b32_e32 v10, v2
	v_mov_b32_e32 v11, v2
	v_mov_b32_e32 v12, v2
	v_mov_b32_e32 v13, v2
	v_mov_b32_e32 v14, v2
	v_mov_b32_e32 v15, v2
	v_mov_b32_e32 v16, v2
	v_mov_b32_e32 v17, v2
	v_mov_b32_e32 v18, v2
	v_mov_b32_e32 v19, v2
	v_mov_b32_e32 v20, v2
	v_mov_b32_e32 v21, v2
	v_mov_b32_e32 v22, v2
	v_mov_b32_e32 v23, v2
	v_mov_b32_e32 v24, v2
	v_mov_b32_e32 v25, v2
	v_mov_b32_e32 v26, v2
	v_mov_b32_e32 v27, v2
	v_mov_b32_e32 v28, v2
	v_mov_b32_e32 v29, v2
	v_mov_b32_e32 v30, v2
	v_mov_b32_e32 v31, v2
	v_mov_b32_e32 v32, v2
	v_mov_b32_e32 v33, v2
	v_mov_b32_e32 v34, v2
	v_mov_b32_e32 v35, v2
	v_mov_b32_e32 v36, v2
	v_mov_b32_e32 v37, v2
	v_mov_b32_e32 v38, v2
	v_mov_b32_e32 v39, v2
	v_mov_b32_e32 v40, v2
	v_mov_b32_e32 v41, v2
	v_mov_b32_e32 v42, v2
	v_mov_b32_e32 v43, v2
	v_mov_b32_e32 v44, v2
	v_mov_b32_e32 v45, v2
	v_mov_b32_e32 v46, v2
	v_mov_b32_e32 v47, v2
	v_mov_b32_e32 v48, v2
	v_mov_b32_e32 v49, v2
	v_mov_b32_e32 v50, v2
	v_mov_b32_e32 v51, v2
	v_mov_b32_e32 v52, v2
	v_mov_b32_e32 v53, v2
	v_mov_b32_e32 v54, v2
	v_mov_b32_e32 v55, v2
	v_mov_b32_e32 v56, v2
	v_mov_b32_e32 v57, v2
	v_mov_b32_e32 v58, v2
	v_mov_b32_e32 v59, v2
	v_mov_b32_e32 v60, v2
	v_mov_b32_e32 v61, v2
	v_mov_b32_e32 v62, v2
	v_mov_b32_e32 v63, v2
	v_mov_b32_e32 v64, v2
	v_mov_b32_e32 v65, v2
	v_mov_b32_e32 v66, v2
	v_mov_b32_e32 v67, v2
	v_mov_b32_e32 v68, v2
	v_mov_b32_e32 v69, v2
	v_mov_b32_e32 v70, v2
	v_mov_b32_e32 v71, v2
	v_mov_b32_e32 v72, v2
	v_mov_b32_e32 v73, v2
	v_mov_b32_e32 v74, v2
	v_mov_b32_e32 v75, v2
	v_mov_b32_e32 v76, v2
	v_mov_b32_e32 v77, v2
	v_mov_b32_e32 v78, v2
	v_mov_b32_e32 v79, v2
	v_mov_b32_e32 v80, v2
	v_mov_b32_e32 v81, v2
	s_waitcnt vmcnt(17)
	v_mov_b32_e32 v82, v2
	v_mov_b32_e32 v83, v2
	v_mov_b32_e32 v84, v2
	v_mov_b32_e32 v85, v2
	s_waitcnt vmcnt(16)
	v_mov_b32_e32 v86, v2
	v_mov_b32_e32 v87, v2
	v_mov_b32_e32 v88, v2
	v_mov_b32_e32 v89, v2
	s_waitcnt vmcnt(15)
	v_mov_b32_e32 v90, v2
	v_mov_b32_e32 v91, v2
	v_mov_b32_e32 v92, v2
	v_mov_b32_e32 v93, v2
	s_waitcnt vmcnt(14)
	v_mov_b32_e32 v94, v2
	v_mov_b32_e32 v95, v2
	v_mov_b32_e32 v96, v2
	v_mov_b32_e32 v97, v2
	v_mov_b32_e32 v98, v2
	v_mov_b32_e32 v99, v2
	v_mov_b32_e32 v100, v2
	v_mov_b32_e32 v101, v2
	v_mov_b32_e32 v102, v2
	v_mov_b32_e32 v103, v2
	v_mov_b32_e32 v104, v2
	v_mov_b32_e32 v105, v2
	v_mov_b32_e32 v106, v2
	v_mov_b32_e32 v107, v2
	v_mov_b32_e32 v108, v2
	v_mov_b32_e32 v109, v2
	v_mov_b32_e32 v110, v2
	v_mov_b32_e32 v111, v2
	v_mov_b32_e32 v112, v2
	v_mov_b32_e32 v113, v2
	v_mov_b32_e32 v114, v2
	v_mov_b32_e32 v115, v2
	v_mov_b32_e32 v116, v2
	v_mov_b32_e32 v117, v2
	v_mov_b32_e32 v118, v2
	v_mov_b32_e32 v119, v2
	v_mov_b32_e32 v120, v2
	v_mov_b32_e32 v121, v2
	v_mov_b32_e32 v122, v2
	v_mov_b32_e32 v123, v2
	v_mov_b32_e32 v124, v2
	v_mov_b32_e32 v125, v2
	v_mov_b32_e32 v126, v2
	v_mov_b32_e32 v127, v2
	v_mov_b32_e32 v128, v2
	v_mov_b32_e32 v129, v2
	s_waitcnt lgkmcnt(0)
	s_mov_b32 s6, 0
	s_mov_b32 s7, 0
	v_mov_b32_e32 v138, v132
	v_mov_b32_e32 v139, v133
	s_waitcnt vmcnt(12)
	s_barrier
	ds_read_b128 v[162:165], v138 offset:0
	ds_read_b128 v[228:231], v139 offset:0
	ds_read_b128 v[236:239], v139 offset:2048
	ds_read_b128 v[204:207], v138 offset:2048
	ds_read_b128 v[212:215], v138 offset:4096
	ds_read_b128 v[220:223], v138 offset:6144
.Lg432_loop:
	v_add_u32_e32 v136, s7, v134
	v_add_u32_e32 v137, s7, v135
	s_add_i32 s6, s6, 1
	s_add_u32 s73, s7, 0x6000
	s_cmp_lt_u32 s73, 0x12000
	s_cselect_b32 s73, s73, 0
	v_add_u32_e32 v138, s73, v132
	v_add_u32_e32 v139, s73, v133
	s_waitcnt lgkmcnt(0)
	v_mfma_f32_32x32x16_bf16 v[114:129], v[162:165], v[228:231], v[114:129]
	ds_read_b128 v[166:169], v136 offset:0
	ds_read_b128 v[232:235], v137 offset:0
	s_add_i32 s14, s6, 2
	s_lshl_b64 s[12:13], s[14:15], 14
	s_add_u32 s12, s12, s74
	v_mfma_f32_32x32x16_bf16 v[98:113], v[162:165], v[236:239], v[98:113]
	ds_read_b128 v[240:243], v137 offset:2048
	ds_read_b128 v[208:211], v136 offset:2048
	s_addc_u32 s13, s13, s75
	v_mfma_f32_32x32x16_bf16 v[82:97], v[204:207], v[228:231], v[82:97]
	ds_read_b128 v[216:219], v136 offset:4096
	ds_read_b128 v[224:227], v136 offset:6144
	v_mfma_f32_32x32x16_bf16 v[66:81], v[204:207], v[236:239], v[66:81]
	v_mfma_f32_32x32x16_bf16 v[50:65], v[212:215], v[228:231], v[50:65]
	v_mfma_f32_32x32x16_bf16 v[34:49], v[212:215], v[236:239], v[34:49]
	v_mfma_f32_32x32x16_bf16 v[18:33], v[220:223], v[228:231], v[18:33]
	v_mfma_f32_32x32x16_bf16 v[2:17], v[220:223], v[236:239], v[2:17]
	s_waitcnt vmcnt(6) lgkmcnt(0)
	s_barrier
	s_add_u32 m0, s7, s72
	v_mfma_f32_32x32x16_bf16 v[114:129], v[166:169], v[232:235], v[114:129]
	ds_read_b128 v[162:165], v138 offset:0
	ds_read_b128 v[228:231], v139 offset:0
	v_mfma_f32_32x32x16_bf16 v[98:113], v[166:169], v[240:243], v[98:113]
	ds_read_b128 v[236:239], v139 offset:2048
	ds_read_b128 v[204:207], v138 offset:2048
	v_mfma_f32_32x32x16_bf16 v[82:97], v[208:211], v[232:235], v[82:97]
	ds_read_b128 v[212:215], v138 offset:4096
	ds_read_b128 v[220:223], v138 offset:6144
	v_mfma_f32_32x32x16_bf16 v[66:81], v[208:211], v[240:243], v[66:81]
	global_load_lds_dwordx4 v140, s[12:13]
	s_add_u32 m0, m0, 0x1000
	s_add_u32 s12, s12, 0x1000
	s_addc_u32 s13, s13, 0
	v_mfma_f32_32x32x16_bf16 v[50:65], v[216:219], v[232:235], v[50:65]
	global_load_lds_dwordx4 v140, s[12:13]
	s_add_u32 m0, m0, 0x1000
	s_add_u32 s12, s12, 0x1000
	s_addc_u32 s13, s13, 0
	v_mfma_f32_32x32x16_bf16 v[34:49], v[216:219], v[240:243], v[34:49]
	global_load_lds_dwordx4 v140, s[12:13]
	s_add_u32 m0, m0, 0x1000
	s_add_u32 s12, s12, 0x1000
	s_addc_u32 s13, s13, 0
	v_mfma_f32_32x32x16_bf16 v[18:33], v[224:227], v[232:235], v[18:33]
	global_load_lds_dwordx4 v140, s[12:13]
	s_add_u32 m0, m0, 0x1000
	s_lshl_b64 s[12:13], s[14:15], 13
	s_add_u32 s12, s12, s76
	s_addc_u32 s13, s13, s77
	v_mfma_f32_32x32x16_bf16 v[2:17], v[224:227], v[240:243], v[2:17]
	global_load_lds_dwordx4 v140, s[12:13]
	s_add_u32 m0, m0, 0x1000
	s_add_u32 s12, s12, 0x1000
	s_addc_u32 s13, s13, 0
	s_nop 0
	global_load_lds_dwordx4 v140, s[12:13]
	s_mov_b32 s7, s73
	s_cmp_lg_u32 s6, 29
	s_cbranch_scc1 .Lg432_loop
	v_add_u32_e32 v136, s7, v134
	v_add_u32_e32 v137, s7, v135
	s_add_i32 s6, s6, 1
	s_add_u32 s73, s7, 0x6000
	s_cmp_lt_u32 s73, 0x12000
	s_cselect_b32 s73, s73, 0
	v_add_u32_e32 v138, s73, v132
	v_add_u32_e32 v139, s73, v133
	s_waitcnt lgkmcnt(0)
	v_mfma_f32_32x32x16_bf16 v[114:129], v[162:165], v[228:231], v[114:129]
	ds_read_b128 v[166:169], v136 offset:0
	ds_read_b128 v[232:235], v137 offset:0
	v_mfma_f32_32x32x16_bf16 v[98:113], v[162:165], v[236:239], v[98:113]
	ds_read_b128 v[240:243], v137 offset:2048
	ds_read_b128 v[208:211], v136 offset:2048
	v_mfma_f32_32x32x16_bf16 v[82:97], v[204:207], v[228:231], v[82:97]
	ds_read_b128 v[216:219], v136 offset:4096
	ds_read_b128 v[224:227], v136 offset:6144
	v_mfma_f32_32x32x16_bf16 v[66:81], v[204:207], v[236:239], v[66:81]
	v_mfma_f32_32x32x16_bf16 v[50:65], v[212:215], v[228:231], v[50:65]
	v_mfma_f32_32x32x16_bf16 v[34:49], v[212:215], v[236:239], v[34:49]
	v_mfma_f32_32x32x16_bf16 v[18:33], v[220:223], v[228:231], v[18:33]
	v_mfma_f32_32x32x16_bf16 v[2:17], v[220:223], v[236:239], v[2:17]
	s_waitcnt vmcnt(6) lgkmcnt(0)
	s_barrier
	v_mfma_f32_32x32x16_bf16 v[114:129], v[166:169], v[232:235], v[114:129]
	ds_read_b128 v[162:165], v138 offset:0
	ds_read_b128 v[228:231], v139 offset:0
	v_mfma_f32_32x32x16_bf16 v[98:113], v[166:169], v[240:243], v[98:113]
	ds_read_b128 v[236:239], v139 offset:2048
	ds_read_b128 v[204:207], v138 offset:2048
	v_mfma_f32_32x32x16_bf16 v[82:97], v[208:211], v[232:235], v[82:97]
	ds_read_b128 v[212:215], v138 offset:4096
	ds_read_b128 v[220:223], v138 offset:6144
	v_mfma_f32_32x32x16_bf16 v[66:81], v[208:211], v[240:243], v[66:81]
	v_mfma_f32_32x32x16_bf16 v[50:65], v[216:219], v[232:235], v[50:65]
	v_mfma_f32_32x32x16_bf16 v[34:49], v[216:219], v[240:243], v[34:49]
	v_mfma_f32_32x32x16_bf16 v[18:33], v[224:227], v[232:235], v[18:33]
	v_mfma_f32_32x32x16_bf16 v[2:17], v[224:227], v[240:243], v[2:17]
	s_mov_b32 s7, s73
	v_add_u32_e32 v136, s7, v134
	v_add_u32_e32 v137, s7, v135
	s_add_i32 s6, s6, 1
	s_add_u32 s73, s7, 0x6000
	s_cmp_lt_u32 s73, 0x12000
	s_cselect_b32 s73, s73, 0
	v_add_u32_e32 v138, s73, v132
	v_add_u32_e32 v139, s73, v133
	s_waitcnt lgkmcnt(0)
	v_mfma_f32_32x32x16_bf16 v[114:129], v[162:165], v[228:231], v[114:129]
	ds_read_b128 v[166:169], v136 offset:0
	ds_read_b128 v[232:235], v137 offset:0
	v_mfma_f32_32x32x16_bf16 v[98:113], v[162:165], v[236:239], v[98:113]
	ds_read_b128 v[240:243], v137 offset:2048
	ds_read_b128 v[208:211], v136 offset:2048
	v_mfma_f32_32x32x16_bf16 v[82:97], v[204:207], v[228:231], v[82:97]
	ds_read_b128 v[216:219], v136 offset:4096
	ds_read_b128 v[224:227], v136 offset:6144
	v_mfma_f32_32x32x16_bf16 v[66:81], v[204:207], v[236:239], v[66:81]
	v_mfma_f32_32x32x16_bf16 v[50:65], v[212:215], v[228:231], v[50:65]
	v_mfma_f32_32x32x16_bf16 v[34:49], v[212:215], v[236:239], v[34:49]
	v_mfma_f32_32x32x16_bf16 v[18:33], v[220:223], v[228:231], v[18:33]
	v_mfma_f32_32x32x16_bf16 v[2:17], v[220:223], v[236:239], v[2:17]
	s_waitcnt vmcnt(0) lgkmcnt(0)
	s_barrier
	v_mfma_f32_32x32x16_bf16 v[114:129], v[166:169], v[232:235], v[114:129]
	ds_read_b128 v[162:165], v138 offset:0
	ds_read_b128 v[228:231], v139 offset:0
	v_mfma_f32_32x32x16_bf16 v[98:113], v[166:169], v[240:243], v[98:113]
	ds_read_b128 v[236:239], v139 offset:2048
	ds_read_b128 v[204:207], v138 offset:2048
	v_mfma_f32_32x32x16_bf16 v[82:97], v[208:211], v[232:235], v[82:97]
	ds_read_b128 v[212:215], v138 offset:4096
	ds_read_b128 v[220:223], v138 offset:6144
	v_mfma_f32_32x32x16_bf16 v[66:81], v[208:211], v[240:243], v[66:81]
	v_mfma_f32_32x32x16_bf16 v[50:65], v[216:219], v[232:235], v[50:65]
	v_mfma_f32_32x32x16_bf16 v[34:49], v[216:219], v[240:243], v[34:49]
	v_mfma_f32_32x32x16_bf16 v[18:33], v[224:227], v[232:235], v[18:33]
	v_mfma_f32_32x32x16_bf16 v[2:17], v[224:227], v[240:243], v[2:17]
	s_mov_b32 s7, s73
	v_add_u32_e32 v136, s7, v134
	v_add_u32_e32 v137, s7, v135
	s_add_i32 s6, s6, 1
	s_waitcnt lgkmcnt(0)
	v_mfma_f32_32x32x16_bf16 v[114:129], v[162:165], v[228:231], v[114:129]
	ds_read_b128 v[166:169], v136 offset:0
	ds_read_b128 v[232:235], v137 offset:0
	v_mfma_f32_32x32x16_bf16 v[98:113], v[162:165], v[236:239], v[98:113]
	ds_read_b128 v[240:243], v137 offset:2048
	ds_read_b128 v[208:211], v136 offset:2048
	v_mfma_f32_32x32x16_bf16 v[82:97], v[204:207], v[228:231], v[82:97]
	ds_read_b128 v[216:219], v136 offset:4096
	ds_read_b128 v[224:227], v136 offset:6144
	v_mfma_f32_32x32x16_bf16 v[66:81], v[204:207], v[236:239], v[66:81]
	v_mfma_f32_32x32x16_bf16 v[50:65], v[212:215], v[228:231], v[50:65]
	v_mfma_f32_32x32x16_bf16 v[34:49], v[212:215], v[236:239], v[34:49]
	v_mfma_f32_32x32x16_bf16 v[18:33], v[220:223], v[228:231], v[18:33]
	v_mfma_f32_32x32x16_bf16 v[2:17], v[220:223], v[236:239], v[2:17]
	s_waitcnt lgkmcnt(0)
	v_mfma_f32_32x32x16_bf16 v[114:129], v[166:169], v[232:235], v[114:129]
	v_mfma_f32_32x32x16_bf16 v[98:113], v[166:169], v[240:243], v[98:113]
	v_mfma_f32_32x32x16_bf16 v[82:97], v[208:211], v[232:235], v[82:97]
	v_mfma_f32_32x32x16_bf16 v[66:81], v[208:211], v[240:243], v[66:81]
	v_mfma_f32_32x32x16_bf16 v[50:65], v[216:219], v[232:235], v[50:65]
	v_mfma_f32_32x32x16_bf16 v[34:49], v[216:219], v[240:243], v[34:49]
	v_mfma_f32_32x32x16_bf16 v[18:33], v[224:227], v[232:235], v[18:33]
	v_mfma_f32_32x32x16_bf16 v[2:17], v[224:227], v[240:243], v[2:17]
	s_mov_b32 s14, 31
	s_lshl_b64 s[12:13], s[14:15], 13
	s_movk_i32 s7, 0x7800
	s_movk_i32 s72, 0x6000
	s_mov_b32 s73, 0xc000
	s_movk_i32 s74, 0x104
	s_mov_b32 s75, 0x42ce8ed0
	s_mov_b32 s76, 0xbfb8aa3b
	s_mov_b32 s77, 0x1d730000
	v_mov_b32_e32 v0, v171
	s_barrier
	s_movk_i32 s0, 0x210
	s_waitcnt vmcnt(4)
	v_lshrrev_b32_e32 v130, 1, v0
	v_and_b32_e32 v130, 0xfffffc0, v130
	v_lshrrev_b32_e32 v131, 3, v0
	v_and_or_b32 v130, v131, 4, v130
	v_and_b32_e32 v0, 0x5f, v0
	v_mul_lo_u32 v130, v130, s0
	v_lshl_add_u32 v0, v0, 2, v130
	s_barrier
	ds_write2_b32 v0, v114, v98 offset1:32
	ds_write2_b32 v0, v115, v99 offset0:132 offset1:164
	v_add_u32_e32 v98, 0x400, v0
	ds_write2_b32 v98, v116, v100 offset0:8 offset1:40
	ds_write2_b32 v98, v117, v101 offset0:140 offset1:172
	v_add_u32_e32 v98, 0x1000, v0
	ds_write2_b32 v98, v118, v102 offset0:32 offset1:64
	ds_write2_b32 v98, v119, v103 offset0:164 offset1:196
	v_add_u32_e32 v98, 0x1400, v0
	ds_write2_b32 v98, v120, v104 offset0:40 offset1:72
	ds_write2_b32 v98, v121, v105 offset0:172 offset1:204
	v_add_u32_e32 v98, 0x2000, v0
	ds_write2_b32 v98, v122, v106 offset0:64 offset1:96
	ds_write2_b32 v98, v123, v107 offset0:196 offset1:228
	v_add_u32_e32 v98, 0x2400, v0
	ds_write2_b32 v98, v124, v108 offset0:72 offset1:104
	ds_write2_b32 v98, v125, v109 offset0:204 offset1:236
	v_add_u32_e32 v98, 0x3000, v0
	ds_write2_b32 v98, v126, v110 offset0:96 offset1:128
	v_add_u32_e32 v98, 0x3200, v0
	ds_write2_b32 v98, v127, v111 offset0:100 offset1:132
	v_add_u32_e32 v98, 0x3400, v0
	ds_write2_b32 v98, v128, v112 offset0:104 offset1:136
	v_add_u32_e32 v98, 0x3600, v0
	ds_write2_b32 v98, v129, v113 offset0:108 offset1:140
	v_add_u32_e32 v98, 0x4000, v0
	ds_write2_b32 v98, v82, v66 offset0:128 offset1:160
	v_add_u32_e32 v66, 0x4400, v0
	ds_write2_b32 v66, v83, v67 offset0:4 offset1:36
	ds_write2_b32 v66, v84, v68 offset0:136 offset1:168
	v_add_u32_e32 v66, 0x4800, v0
	ds_write2_b32 v66, v85, v69 offset0:12 offset1:44
	v_add_u32_e32 v66, 0x5000, v0
	ds_write2_b32 v66, v86, v70 offset0:160 offset1:192
	v_add_u32_e32 v66, 0x5400, v0
	ds_write2_b32 v66, v87, v71 offset0:36 offset1:68
	ds_write2_b32 v66, v88, v72 offset0:168 offset1:200
	v_add_u32_e32 v66, 0x5800, v0
	ds_write2_b32 v66, v89, v73 offset0:44 offset1:76
	v_add_u32_e32 v66, 0x6000, v0
	ds_write2_b32 v66, v90, v74 offset0:192 offset1:224
	v_add_u32_e32 v66, 0x6400, v0
	ds_write2_b32 v66, v91, v75 offset0:68 offset1:100
	ds_write2_b32 v66, v92, v76 offset0:200 offset1:232
	v_add_u32_e32 v66, 0x6800, v0
	ds_write2_b32 v66, v93, v77 offset0:76 offset1:108
	v_add_u32_e32 v66, 0x7200, v0
	ds_write2_b32 v66, v94, v78 offset0:96 offset1:128
	v_add_u32_e32 v66, 0x7400, v0
	s_lshr_b32 s14, s42, 2
	ds_write2_b32 v66, v95, v79 offset0:100 offset1:132
	v_add_u32_e32 v66, 0x7600, v0
	v_add_u32_e32 v0, 0x7800, v0
	v_mov_b32_e32 v105, v171
	s_cmp_lt_i32 s14, 14
	s_mov_b64 s[6:7], -1
	ds_write2_b32 v66, v96, v80 offset0:104 offset1:136
	ds_write2_b32 v0, v97, v81 offset0:108 offset1:140
	s_waitcnt lgkmcnt(0)
	s_barrier
	s_cbranch_scc1 .LBB0_439
	s_cmp_gt_i32 s14, 14
	s_cbranch_scc0 .LBB0_436
	s_mov_b64 s[6:7], 0

.LBB0_587:
	s_lshr_b32 s6, s8, 3
	s_and_b32 s9, s8, 56
	v_readlane_b32 s0, v252, 42
	s_and_b32 s6, s6, 0xffffff8
	s_and_b32 s7, s8, 7
	s_or_b32 s10, s9, s0
	v_mov_b32_e32 v6, v171
	s_or_b32 s6, s6, s7
	s_lshl_b32 s7, s10, 21
	v_readlane_b32 s0, v252, 46
	v_lshlrev_b32_e32 v2, 3, v6
	v_readlane_b32 s1, v252, 47
	s_add_u32 s12, s0, s7
	v_ashrrev_i32_e32 v3, 31, v2
	s_addc_u32 s13, s1, 0
	v_lshlrev_b64 v[4:5], 1, v[2:3]
	s_mov_b32 s7, s15
	v_lshl_add_u64 v[154:155], s[12:13], 0, v[4:5]
	s_mov_b64 s[74:75], s[12:13]
	s_lshl_b64 s[12:13], s[6:7], 20
	v_readlane_b32 s0, v252, 34
	v_readlane_b32 s1, v252, 35
	s_add_u32 s12, s0, s12
	s_addc_u32 s13, s1, s13
	v_lshrrev_b32_e32 v3, 2, v6
	v_and_b32_e32 v0, 24, v2
	v_lshl_add_u64 v[156:157], s[12:13], 0, v[4:5]
	s_mov_b64 s[76:77], s[12:13]
	v_mad_u64_u32 v[158:159], s[12:13], v3, 40, v[0:1]
	s_movk_i32 s0, 0x50
	v_and_b32_e32 v2, 0x30, v6
	v_xor_b32_e32 v140, v4, v2
	v_xor_b32_e32 v154, v154, v2
	v_xor_b32_e32 v156, v156, v2
	v_and_b32_e32 v130, 31, v6
	v_lshlrev_b32_e32 v130, 6, v130
	v_lshrrev_b32_e32 v131, 2, v6
	v_and_b32_e32 v131, 3, v131
	v_bfe_u32 v133, v6, 5, 1
	v_xor_b32_e32 v131, v131, v133
	v_lshl_or_b32 v130, v131, 4, v130
	v_lshrrev_b32_e32 v131, 7, v6
	v_lshl_or_b32 v132, v131, 13, v130
	v_bfe_u32 v131, v6, 6, 1
	v_lshl_or_b32 v133, v131, 12, v130
	v_or_b32_e32 v133, 0x4000, v133
	v_xor_b32_e32 v134, 32, v132
	v_xor_b32_e32 v135, 32, v133
	v_lshrrev_b32_e32 v131, 6, v6
	s_nop 1
	v_readfirstlane_b32 s72, v131
	s_nop 3
	s_lshl_b32 s72, s72, 10
	s_waitcnt lgkmcnt(0)
	s_barrier
	s_mov_b32 s14, 0
	s_lshl_b64 s[12:13], s[14:15], 14
	s_add_u32 s12, s12, s74
	s_addc_u32 s13, s13, s75
	s_add_u32 m0, s72, 0x0
	s_nop 0
	global_load_lds_dwordx4 v140, s[12:13]
	s_add_u32 m0, m0, 0x1000
	s_add_u32 s12, s12, 0x1000
	s_addc_u32 s13, s13, 0
	global_load_lds_dwordx4 v140, s[12:13]
	s_add_u32 m0, m0, 0x1000
	s_add_u32 s12, s12, 0x1000
	s_addc_u32 s13, s13, 0
	global_load_lds_dwordx4 v140, s[12:13]
	s_add_u32 m0, m0, 0x1000
	s_add_u32 s12, s12, 0x1000
	s_addc_u32 s13, s13, 0
	global_load_lds_dwordx4 v140, s[12:13]
	s_add_u32 m0, m0, 0x1000
	s_lshl_b64 s[12:13], s[14:15], 13
	s_add_u32 s12, s12, s76
	s_addc_u32 s13, s13, s77
	global_load_lds_dwordx4 v140, s[12:13]
	s_add_u32 m0, m0, 0x1000
	s_add_u32 s12, s12, 0x1000
	s_addc_u32 s13, s13, 0
	global_load_lds_dwordx4 v140, s[12:13]
	s_mov_b32 s14, 1
	s_lshl_b64 s[12:13], s[14:15], 14
	s_add_u32 s12, s12, s74
	s_addc_u32 s13, s13, s75
	s_add_u32 m0, s72, 0x6000
	s_nop 0
	global_load_lds_dwordx4 v140, s[12:13]
	s_add_u32 m0, m0, 0x1000
	s_add_u32 s12, s12, 0x1000
	s_addc_u32 s13, s13, 0
	global_load_lds_dwordx4 v140, s[12:13]
	s_add_u32 m0, m0, 0x1000
	s_add_u32 s12, s12, 0x1000
	s_addc_u32 s13, s13, 0
	global_load_lds_dwordx4 v140, s[12:13]
	s_add_u32 m0, m0, 0x1000
	s_add_u32 s12, s12, 0x1000
	s_addc_u32 s13, s13, 0
	global_load_lds_dwordx4 v140, s[12:13]
	s_add_u32 m0, m0, 0x1000
	s_lshl_b64 s[12:13], s[14:15], 13
	s_add_u32 s12, s12, s76
	s_addc_u32 s13, s13, s77
	global_load_lds_dwordx4 v140, s[12:13]
	s_add_u32 m0, m0, 0x1000
	s_add_u32 s12, s12, 0x1000
	s_addc_u32 s13, s13, 0
	global_load_lds_dwordx4 v140, s[12:13]
	s_mov_b32 s14, 2
	s_lshl_b64 s[12:13], s[14:15], 14
	s_add_u32 s12, s12, s74
	s_addc_u32 s13, s13, s75
	s_add_u32 m0, s72, 0xc000
	s_nop 0
	global_load_lds_dwordx4 v140, s[12:13]
	s_add_u32 m0, m0, 0x1000
	s_add_u32 s12, s12, 0x1000
	s_addc_u32 s13, s13, 0
	global_load_lds_dwordx4 v140, s[12:13]
	s_add_u32 m0, m0, 0x1000
	s_add_u32 s12, s12, 0x1000
	s_addc_u32 s13, s13, 0
	global_load_lds_dwordx4 v140, s[12:13]
	s_add_u32 m0, m0, 0x1000
	s_add_u32 s12, s12, 0x1000
	s_addc_u32 s13, s13, 0
	global_load_lds_dwordx4 v140, s[12:13]
	s_add_u32 m0, m0, 0x1000
	s_lshl_b64 s[12:13], s[14:15], 13
	s_add_u32 s12, s12, s76
	s_addc_u32 s13, s13, s77
	global_load_lds_dwordx4 v140, s[12:13]
	s_add_u32 m0, m0, 0x1000
	s_add_u32 s12, s12, 0x1000
	s_addc_u32 s13, s13, 0
	global_load_lds_dwordx4 v140, s[12:13]
	v_and_b32_e32 v2, 0xfffff9f, v6
	v_mul_lo_u32 v160, v2, s0
	v_or_b32_e32 v2, 0x60, v6
	v_lshrrev_b32_e32 v0, 1, v6
	v_and_b32_e32 v3, 0x5f, v6
	v_mul_lo_u32 v161, v2, s0
	v_mov_b32_e32 v2, 0
	s_mov_b32 s7, 0
	v_and_b32_e32 v0, 16, v0
	v_mul_u32_u24_e32 v159, 0x50, v3
	v_mov_b32_e32 v3, v2
	v_mov_b32_e32 v4, v2
	v_mov_b32_e32 v5, v2
	v_mov_b32_e32 v6, v2
	v_mov_b32_e32 v7, v2
	v_mov_b32_e32 v8, v2
	v_mov_b32_e32 v9, v2
	v_mov_b32_e32 v10, v2
	v_mov_b32_e32 v11, v2
	v_mov_b32_e32 v12, v2
	v_mov_b32_e32 v13, v2
	v_mov_b32_e32 v14, v2
	v_mov_b32_e32 v15, v2
	v_mov_b32_e32 v16, v2
	v_mov_b32_e32 v17, v2
	v_mov_b32_e32 v18, v2
	v_mov_b32_e32 v19, v2
	v_mov_b32_e32 v20, v2
	v_mov_b32_e32 v21, v2
	v_mov_b32_e32 v22, v2
	v_mov_b32_e32 v23, v2
	v_mov_b32_e32 v24, v2
	v_mov_b32_e32 v25, v2
	v_mov_b32_e32 v26, v2
	v_mov_b32_e32 v27, v2
	v_mov_b32_e32 v28, v2
	v_mov_b32_e32 v29, v2
	v_mov_b32_e32 v30, v2
	v_mov_b32_e32 v31, v2
	v_mov_b32_e32 v32, v2
	v_mov_b32_e32 v33, v2
	v_mov_b32_e32 v34, v2
	v_mov_b32_e32 v35, v2
	v_mov_b32_e32 v36, v2
	v_mov_b32_e32 v37, v2
	v_mov_b32_e32 v38, v2
	v_mov_b32_e32 v39, v2
	v_mov_b32_e32 v40, v2
	v_mov_b32_e32 v41, v2
	v_mov_b32_e32 v42, v2
	v_mov_b32_e32 v43, v2
	v_mov_b32_e32 v44, v2
	v_mov_b32_e32 v45, v2
	v_mov_b32_e32 v46, v2
	v_mov_b32_e32 v47, v2
	v_mov_b32_e32 v48, v2
	v_mov_b32_e32 v49, v2
	v_mov_b32_e32 v50, v2
	v_mov_b32_e32 v51, v2
	v_mov_b32_e32 v52, v2
	v_mov_b32_e32 v53, v2
	v_mov_b32_e32 v54, v2
	v_mov_b32_e32 v55, v2
	v_mov_b32_e32 v56, v2
	v_mov_b32_e32 v57, v2
	v_mov_b32_e32 v58, v2
	v_mov_b32_e32 v59, v2
	v_mov_b32_e32 v60, v2
	v_mov_b32_e32 v61, v2
	v_mov_b32_e32 v62, v2
	v_mov_b32_e32 v63, v2
	v_mov_b32_e32 v64, v2
	v_mov_b32_e32 v65, v2
	v_mov_b32_e32 v66, v2
	v_mov_b32_e32 v67, v2
	v_mov_b32_e32 v68, v2
	v_mov_b32_e32 v69, v2
	v_mov_b32_e32 v70, v2
	v_mov_b32_e32 v71, v2
	v_mov_b32_e32 v72, v2
	v_mov_b32_e32 v73, v2
	v_mov_b32_e32 v74, v2
	v_mov_b32_e32 v75, v2
	v_mov_b32_e32 v76, v2
	v_mov_b32_e32 v77, v2
	v_mov_b32_e32 v78, v2
	v_mov_b32_e32 v79, v2
	v_mov_b32_e32 v80, v2
	v_mov_b32_e32 v81, v2
	s_waitcnt vmcnt(17)
	v_mov_b32_e32 v82, v2
	v_mov_b32_e32 v83, v2
	v_mov_b32_e32 v84, v2
	v_mov_b32_e32 v85, v2
	s_waitcnt vmcnt(16)
	v_mov_b32_e32 v86, v2
	v_mov_b32_e32 v87, v2
	v_mov_b32_e32 v88, v2
	v_mov_b32_e32 v89, v2
	s_waitcnt vmcnt(15)
	v_mov_b32_e32 v90, v2
	v_mov_b32_e32 v91, v2
	v_mov_b32_e32 v92, v2
	v_mov_b32_e32 v93, v2
	s_waitcnt vmcnt(14)
	v_mov_b32_e32 v94, v2
	v_mov_b32_e32 v95, v2
	v_mov_b32_e32 v96, v2
	v_mov_b32_e32 v97, v2
	v_mov_b32_e32 v98, v2
	v_mov_b32_e32 v99, v2
	v_mov_b32_e32 v100, v2
	v_mov_b32_e32 v101, v2
	v_mov_b32_e32 v102, v2
	v_mov_b32_e32 v103, v2
	v_mov_b32_e32 v104, v2
	v_mov_b32_e32 v105, v2
	v_mov_b32_e32 v106, v2
	v_mov_b32_e32 v107, v2
	v_mov_b32_e32 v108, v2
	v_mov_b32_e32 v109, v2
	v_mov_b32_e32 v110, v2
	v_mov_b32_e32 v111, v2
	v_mov_b32_e32 v112, v2
	v_mov_b32_e32 v113, v2
	v_mov_b32_e32 v114, v2
	v_mov_b32_e32 v115, v2
	v_mov_b32_e32 v116, v2
	v_mov_b32_e32 v117, v2
	v_mov_b32_e32 v118, v2
	v_mov_b32_e32 v119, v2
	v_mov_b32_e32 v120, v2
	v_mov_b32_e32 v121, v2
	v_mov_b32_e32 v122, v2
	v_mov_b32_e32 v123, v2
	v_mov_b32_e32 v124, v2
	v_mov_b32_e32 v125, v2
	v_mov_b32_e32 v126, v2
	v_mov_b32_e32 v127, v2
	v_mov_b32_e32 v128, v2
	v_mov_b32_e32 v129, v2
	s_waitcnt lgkmcnt(0)
	s_mov_b32 s7, 0
	s_mov_b32 s11, 0
	v_mov_b32_e32 v138, v132
	v_mov_b32_e32 v139, v133
	s_waitcnt vmcnt(12)
	s_barrier
	ds_read_b128 v[162:165], v138 offset:0
	ds_read_b128 v[228:231], v139 offset:0
	ds_read_b128 v[236:239], v139 offset:2048
	ds_read_b128 v[204:207], v138 offset:2048
	ds_read_b128 v[212:215], v138 offset:4096
	ds_read_b128 v[220:223], v138 offset:6144
.Lg588_loop:
	v_add_u32_e32 v136, s11, v134
	v_add_u32_e32 v137, s11, v135
	s_add_i32 s7, s7, 1
	s_add_u32 s73, s11, 0x6000
	s_cmp_lt_u32 s73, 0x12000
	s_cselect_b32 s73, s73, 0
	v_add_u32_e32 v138, s73, v132
	v_add_u32_e32 v139, s73, v133
	s_waitcnt lgkmcnt(0)
	v_mfma_f32_32x32x16_bf16 v[114:129], v[162:165], v[228:231], v[114:129]
	ds_read_b128 v[166:169], v136 offset:0
	ds_read_b128 v[232:235], v137 offset:0
	s_add_i32 s14, s7, 2
	s_lshl_b64 s[12:13], s[14:15], 14
	s_add_u32 s12, s12, s74
	v_mfma_f32_32x32x16_bf16 v[98:113], v[162:165], v[236:239], v[98:113]
	ds_read_b128 v[240:243], v137 offset:2048
	ds_read_b128 v[208:211], v136 offset:2048
	s_addc_u32 s13, s13, s75
	v_mfma_f32_32x32x16_bf16 v[82:97], v[204:207], v[228:231], v[82:97]
	ds_read_b128 v[216:219], v136 offset:4096
	ds_read_b128 v[224:227], v136 offset:6144
	v_mfma_f32_32x32x16_bf16 v[66:81], v[204:207], v[236:239], v[66:81]
	v_mfma_f32_32x32x16_bf16 v[50:65], v[212:215], v[228:231], v[50:65]
	v_mfma_f32_32x32x16_bf16 v[34:49], v[212:215], v[236:239], v[34:49]
	v_mfma_f32_32x32x16_bf16 v[18:33], v[220:223], v[228:231], v[18:33]
	v_mfma_f32_32x32x16_bf16 v[2:17], v[220:223], v[236:239], v[2:17]
	s_waitcnt vmcnt(6) lgkmcnt(0)
	s_barrier
	s_add_u32 m0, s11, s72
	v_mfma_f32_32x32x16_bf16 v[114:129], v[166:169], v[232:235], v[114:129]
	ds_read_b128 v[162:165], v138 offset:0
	ds_read_b128 v[228:231], v139 offset:0
	v_mfma_f32_32x32x16_bf16 v[98:113], v[166:169], v[240:243], v[98:113]
	ds_read_b128 v[236:239], v139 offset:2048
	ds_read_b128 v[204:207], v138 offset:2048
	v_mfma_f32_32x32x16_bf16 v[82:97], v[208:211], v[232:235], v[82:97]
	ds_read_b128 v[212:215], v138 offset:4096
	ds_read_b128 v[220:223], v138 offset:6144
	v_mfma_f32_32x32x16_bf16 v[66:81], v[208:211], v[240:243], v[66:81]
	global_load_lds_dwordx4 v140, s[12:13]
	s_add_u32 m0, m0, 0x1000
	s_add_u32 s12, s12, 0x1000
	s_addc_u32 s13, s13, 0
	v_mfma_f32_32x32x16_bf16 v[50:65], v[216:219], v[232:235], v[50:65]
	global_load_lds_dwordx4 v140, s[12:13]
	s_add_u32 m0, m0, 0x1000
	s_add_u32 s12, s12, 0x1000
	s_addc_u32 s13, s13, 0
	v_mfma_f32_32x32x16_bf16 v[34:49], v[216:219], v[240:243], v[34:49]
	global_load_lds_dwordx4 v140, s[12:13]
	s_add_u32 m0, m0, 0x1000
	s_add_u32 s12, s12, 0x1000
	s_addc_u32 s13, s13, 0
	v_mfma_f32_32x32x16_bf16 v[18:33], v[224:227], v[232:235], v[18:33]
	global_load_lds_dwordx4 v140, s[12:13]
	s_add_u32 m0, m0, 0x1000
	s_lshl_b64 s[12:13], s[14:15], 13
	s_add_u32 s12, s12, s76
	s_addc_u32 s13, s13, s77
	v_mfma_f32_32x32x16_bf16 v[2:17], v[224:227], v[240:243], v[2:17]
	global_load_lds_dwordx4 v140, s[12:13]
	s_add_u32 m0, m0, 0x1000
	s_add_u32 s12, s12, 0x1000
	s_addc_u32 s13, s13, 0
	s_nop 0
	global_load_lds_dwordx4 v140, s[12:13]
	s_mov_b32 s11, s73
	s_cmp_lg_u32 s7, 125
	s_cbranch_scc1 .Lg588_loop
	v_add_u32_e32 v136, s11, v134
	v_add_u32_e32 v137, s11, v135
	s_add_i32 s7, s7, 1
	s_add_u32 s73, s11, 0x6000
	s_cmp_lt_u32 s73, 0x12000
	s_cselect_b32 s73, s73, 0
	v_add_u32_e32 v138, s73, v132
	v_add_u32_e32 v139, s73, v133
	s_waitcnt lgkmcnt(0)
	v_mfma_f32_32x32x16_bf16 v[114:129], v[162:165], v[228:231], v[114:129]
	ds_read_b128 v[166:169], v136 offset:0
	ds_read_b128 v[232:235], v137 offset:0
	v_mfma_f32_32x32x16_bf16 v[98:113], v[162:165], v[236:239], v[98:113]
	ds_read_b128 v[240:243], v137 offset:2048
	ds_read_b128 v[208:211], v136 offset:2048
	v_mfma_f32_32x32x16_bf16 v[82:97], v[204:207], v[228:231], v[82:97]
	ds_read_b128 v[216:219], v136 offset:4096
	ds_read_b128 v[224:227], v136 offset:6144
	v_mfma_f32_32x32x16_bf16 v[66:81], v[204:207], v[236:239], v[66:81]
	v_mfma_f32_32x32x16_bf16 v[50:65], v[212:215], v[228:231], v[50:65]
	v_mfma_f32_32x32x16_bf16 v[34:49], v[212:215], v[236:239], v[34:49]
	v_mfma_f32_32x32x16_bf16 v[18:33], v[220:223], v[228:231], v[18:33]
	v_mfma_f32_32x32x16_bf16 v[2:17], v[220:223], v[236:239], v[2:17]
	s_waitcnt vmcnt(6) lgkmcnt(0)
	s_barrier
	v_mfma_f32_32x32x16_bf16 v[114:129], v[166:169], v[232:235], v[114:129]
	ds_read_b128 v[162:165], v138 offset:0
	ds_read_b128 v[228:231], v139 offset:0
	v_mfma_f32_32x32x16_bf16 v[98:113], v[166:169], v[240:243], v[98:113]
	ds_read_b128 v[236:239], v139 offset:2048
	ds_read_b128 v[204:207], v138 offset:2048
	v_mfma_f32_32x32x16_bf16 v[82:97], v[208:211], v[232:235], v[82:97]
	ds_read_b128 v[212:215], v138 offset:4096
	ds_read_b128 v[220:223], v138 offset:6144
	v_mfma_f32_32x32x16_bf16 v[66:81], v[208:211], v[240:243], v[66:81]
	v_mfma_f32_32x32x16_bf16 v[50:65], v[216:219], v[232:235], v[50:65]
	v_mfma_f32_32x32x16_bf16 v[34:49], v[216:219], v[240:243], v[34:49]
	v_mfma_f32_32x32x16_bf16 v[18:33], v[224:227], v[232:235], v[18:33]
	v_mfma_f32_32x32x16_bf16 v[2:17], v[224:227], v[240:243], v[2:17]
	s_mov_b32 s11, s73
	v_add_u32_e32 v136, s11, v134
	v_add_u32_e32 v137, s11, v135
	s_add_i32 s7, s7, 1
	s_add_u32 s73, s11, 0x6000
	s_cmp_lt_u32 s73, 0x12000
	s_cselect_b32 s73, s73, 0
	v_add_u32_e32 v138, s73, v132
	v_add_u32_e32 v139, s73, v133
	s_waitcnt lgkmcnt(0)
	v_mfma_f32_32x32x16_bf16 v[114:129], v[162:165], v[228:231], v[114:129]
	ds_read_b128 v[166:169], v136 offset:0
	ds_read_b128 v[232:235], v137 offset:0
	v_mfma_f32_32x32x16_bf16 v[98:113], v[162:165], v[236:239], v[98:113]
	ds_read_b128 v[240:243], v137 offset:2048
	ds_read_b128 v[208:211], v136 offset:2048
	v_mfma_f32_32x32x16_bf16 v[82:97], v[204:207], v[228:231], v[82:97]
	ds_read_b128 v[216:219], v136 offset:4096
	ds_read_b128 v[224:227], v136 offset:6144
	v_mfma_f32_32x32x16_bf16 v[66:81], v[204:207], v[236:239], v[66:81]
	v_mfma_f32_32x32x16_bf16 v[50:65], v[212:215], v[228:231], v[50:65]
	v_mfma_f32_32x32x16_bf16 v[34:49], v[212:215], v[236:239], v[34:49]
	v_mfma_f32_32x32x16_bf16 v[18:33], v[220:223], v[228:231], v[18:33]
	v_mfma_f32_32x32x16_bf16 v[2:17], v[220:223], v[236:239], v[2:17]
	s_waitcnt vmcnt(0) lgkmcnt(0)
	s_barrier
	v_mfma_f32_32x32x16_bf16 v[114:129], v[166:169], v[232:235], v[114:129]
	ds_read_b128 v[162:165], v138 offset:0
	ds_read_b128 v[228:231], v139 offset:0
	v_mfma_f32_32x32x16_bf16 v[98:113], v[166:169], v[240:243], v[98:113]
	ds_read_b128 v[236:239], v139 offset:2048
	ds_read_b128 v[204:207], v138 offset:2048
	v_mfma_f32_32x32x16_bf16 v[82:97], v[208:211], v[232:235], v[82:97]
	ds_read_b128 v[212:215], v138 offset:4096
	ds_read_b128 v[220:223], v138 offset:6144
	v_mfma_f32_32x32x16_bf16 v[66:81], v[208:211], v[240:243], v[66:81]
	v_mfma_f32_32x32x16_bf16 v[50:65], v[216:219], v[232:235], v[50:65]
	v_mfma_f32_32x32x16_bf16 v[34:49], v[216:219], v[240:243], v[34:49]
	v_mfma_f32_32x32x16_bf16 v[18:33], v[224:227], v[232:235], v[18:33]
	v_mfma_f32_32x32x16_bf16 v[2:17], v[224:227], v[240:243], v[2:17]
	s_mov_b32 s11, s73
	v_add_u32_e32 v136, s11, v134
	v_add_u32_e32 v137, s11, v135
	s_add_i32 s7, s7, 1
	s_waitcnt lgkmcnt(0)
	v_mfma_f32_32x32x16_bf16 v[114:129], v[162:165], v[228:231], v[114:129]
	ds_read_b128 v[166:169], v136 offset:0
	ds_read_b128 v[232:235], v137 offset:0
	v_mfma_f32_32x32x16_bf16 v[98:113], v[162:165], v[236:239], v[98:113]
	ds_read_b128 v[240:243], v137 offset:2048
	ds_read_b128 v[208:211], v136 offset:2048
	v_mfma_f32_32x32x16_bf16 v[82:97], v[204:207], v[228:231], v[82:97]
	ds_read_b128 v[216:219], v136 offset:4096
	ds_read_b128 v[224:227], v136 offset:6144
	v_mfma_f32_32x32x16_bf16 v[66:81], v[204:207], v[236:239], v[66:81]
	v_mfma_f32_32x32x16_bf16 v[50:65], v[212:215], v[228:231], v[50:65]
	v_mfma_f32_32x32x16_bf16 v[34:49], v[212:215], v[236:239], v[34:49]
	v_mfma_f32_32x32x16_bf16 v[18:33], v[220:223], v[228:231], v[18:33]
	v_mfma_f32_32x32x16_bf16 v[2:17], v[220:223], v[236:239], v[2:17]
	s_waitcnt lgkmcnt(0)
	v_mfma_f32_32x32x16_bf16 v[114:129], v[166:169], v[232:235], v[114:129]
	v_mfma_f32_32x32x16_bf16 v[98:113], v[166:169], v[240:243], v[98:113]
	v_mfma_f32_32x32x16_bf16 v[82:97], v[208:211], v[232:235], v[82:97]
	v_mfma_f32_32x32x16_bf16 v[66:81], v[208:211], v[240:243], v[66:81]
	v_mfma_f32_32x32x16_bf16 v[50:65], v[216:219], v[232:235], v[50:65]
	v_mfma_f32_32x32x16_bf16 v[34:49], v[216:219], v[240:243], v[34:49]
	v_mfma_f32_32x32x16_bf16 v[18:33], v[224:227], v[232:235], v[18:33]
	v_mfma_f32_32x32x16_bf16 v[2:17], v[224:227], v[240:243], v[2:17]
	s_mov_b32 s14, 127
	s_lshl_b64 s[12:13], s[14:15], 13
	s_movk_i32 s11, 0x7800
	s_movk_i32 s72, 0x6000
	s_mov_b32 s73, 0xc000
	s_movk_i32 s74, 0x104
	s_mov_b32 s75, 0x42ce8ed0
	s_mov_b32 s76, 0xbfb8aa3b
	s_mov_b32 s77, 0x1d730000
	v_mov_b32_e32 v0, v171
	s_barrier
	s_movk_i32 s0, 0x210
	s_waitcnt vmcnt(4)
	v_lshrrev_b32_e32 v130, 1, v0
	v_and_b32_e32 v130, 0xfffffc0, v130
	v_lshrrev_b32_e32 v131, 3, v0
	v_and_or_b32 v130, v131, 4, v130
	v_and_b32_e32 v0, 0x5f, v0
	v_mul_lo_u32 v130, v130, s0
	v_lshl_add_u32 v0, v0, 2, v130
	s_barrier
	ds_write2_b32 v0, v114, v98 offset1:32
	ds_write2_b32 v0, v115, v99 offset0:132 offset1:164
	v_add_u32_e32 v98, 0x400, v0
	ds_write2_b32 v98, v116, v100 offset0:8 offset1:40
	ds_write2_b32 v98, v117, v101 offset0:140 offset1:172
	v_add_u32_e32 v98, 0x1000, v0
	ds_write2_b32 v98, v118, v102 offset0:32 offset1:64
	ds_write2_b32 v98, v119, v103 offset0:164 offset1:196
	v_add_u32_e32 v98, 0x1400, v0
	ds_write2_b32 v98, v120, v104 offset0:40 offset1:72
	ds_write2_b32 v98, v121, v105 offset0:172 offset1:204
	v_add_u32_e32 v98, 0x2000, v0
	ds_write2_b32 v98, v122, v106 offset0:64 offset1:96
	ds_write2_b32 v98, v123, v107 offset0:196 offset1:228
	v_add_u32_e32 v98, 0x2400, v0
	ds_write2_b32 v98, v124, v108 offset0:72 offset1:104
	ds_write2_b32 v98, v125, v109 offset0:204 offset1:236
	v_add_u32_e32 v98, 0x3000, v0
	ds_write2_b32 v98, v126, v110 offset0:96 offset1:128
	v_add_u32_e32 v98, 0x3200, v0
	ds_write2_b32 v98, v127, v111 offset0:100 offset1:132
	v_add_u32_e32 v98, 0x3400, v0
	ds_write2_b32 v98, v128, v112 offset0:104 offset1:136
	v_add_u32_e32 v98, 0x3600, v0
	ds_write2_b32 v98, v129, v113 offset0:108 offset1:140
	v_add_u32_e32 v98, 0x4000, v0
	ds_write2_b32 v98, v82, v66 offset0:128 offset1:160
	v_add_u32_e32 v66, 0x4400, v0
	ds_write2_b32 v66, v83, v67 offset0:4 offset1:36
	ds_write2_b32 v66, v84, v68 offset0:136 offset1:168
	v_add_u32_e32 v66, 0x4800, v0
	ds_write2_b32 v66, v85, v69 offset0:12 offset1:44
	v_add_u32_e32 v66, 0x5000, v0
	s_lshl_b32 s10, s10, 8
	ds_write2_b32 v66, v86, v70 offset0:160 offset1:192
	v_add_u32_e32 v66, 0x5400, v0
	s_lshl_b32 s11, s6, 7
	ds_write2_b32 v66, v87, v71 offset0:36 offset1:68
	ds_write2_b32 v66, v88, v72 offset0:168 offset1:200
	v_add_u32_e32 v66, 0x5800, v0
	s_add_i32 s6, s10, 0xffffe000
	ds_write2_b32 v66, v89, v73 offset0:44 offset1:76
	v_add_u32_e32 v66, 0x6000, v0
	s_lshr_b32 s6, s6, 12
	ds_write2_b32 v66, v90, v74 offset0:192 offset1:224
	v_add_u32_e32 v66, 0x6400, v0
	s_mulk_i32 s6, 0x1800
	ds_write2_b32 v66, v91, v75 offset0:68 offset1:100
	ds_write2_b32 v66, v92, v76 offset0:200 offset1:232
	v_add_u32_e32 v66, 0x6800, v0
	s_addk_i32 s6, 0x1800
	ds_write2_b32 v66, v93, v77 offset0:76 offset1:108
	v_add_u32_e32 v66, 0x7200, v0
	s_cmp_gt_u32 s9, 31
	ds_write2_b32 v66, v94, v78 offset0:96 offset1:128
	v_add_u32_e32 v66, 0x7400, v0
	s_cselect_b32 s14, s6, 0
	ds_write2_b32 v66, v95, v79 offset0:100 offset1:132
	v_add_u32_e32 v66, 0x7600, v0
	v_add_u32_e32 v0, 0x7800, v0
	v_mov_b32_e32 v84, v171
	s_lshl_b64 s[6:7], s[14:15], 2
	ds_write2_b32 v66, v96, v80 offset0:104 offset1:136
	ds_write2_b32 v0, v97, v81 offset0:108 offset1:140
	s_waitcnt lgkmcnt(0)
	s_barrier
	s_add_u32 s6, s61, s6
	v_lshlrev_b32_e32 v0, 3, v84
	v_and_b32_e32 v0, 0x78, v0
	s_addc_u32 s7, s53, s7
	v_or_b32_e32 v0, s11, v0
	s_add_u32 s6, s6, 0x1d645000
	s_addc_u32 s7, s7, 0
	v_lshlrev_b64 v[82:83], 2, v[0:1]
	v_lshl_add_u64 v[70:71], s[6:7], 0, v[82:83]
	v_lshl_add_u64 v[78:79], s[4:5], 0, v[82:83]
	global_load_dwordx4 v[66:69], v[70:71], off offset:16
	s_nop 0
	global_load_dwordx4 v[70:73], v[70:71], off
	s_nop 0
	global_load_dwordx4 v[74:77], v[78:79], off offset:16
	s_nop 0
	global_load_dwordx4 v[78:81], v[78:79], off
	v_ashrrev_i32_e32 v0, 4, v84
	v_mul_lo_u32 v85, v0, s0
	v_and_b32_e32 v84, 15, v84
	s_mov_b32 s9, 0
	v_lshl_add_u64 v[82:83], s[56:57], 0, v[82:83]
	v_lshl_add_u32 v84, v84, 5, v85
	v_lshlrev_b32_e32 v85, 1, v0
